# v_rm_m1 + XA entry: q-tile/stat loads stay in flight across the barrier (hipcc's vmcnt(0) before the first K-fragment read relaxed)
# baseline (speedup 1.0000x reference)
.LBB0_812:
	s_or_b64 exec, exec, s[2:3]
	s_and_b64 vcc, exec, s[50:51]
	s_barrier
	s_cbranch_vccnz .LBB0_814
	s_mov_b32 s2, s87
	s_ashr_i32 s3, s2, 31
	s_lshl_b64 s[2:3], s[2:3], 3
	s_add_u32 s2, s0, s2
	s_addc_u32 s3, s1, s3
	s_mov_b64 s[2:3], s[100:101]
	s_mov_b32 s4, s87
	s_mov_b32 s6, s87
	v_mov_b32_e32 v145, v0
	s_waitcnt lgkmcnt(0)
	s_add_u32 s8, s2, s81
	s_addc_u32 s16, s3, 0
	s_ashr_i32 s5, s4, 31
	s_lshl_b64 s[2:3], s[4:5], 3
	s_add_u32 s2, s0, s2
	s_addc_u32 s3, s1, s3
	s_mov_b64 s[2:3], s[100:101]
	s_mov_b32 s5, s87
	s_mov_b32 s4, s87
	s_waitcnt lgkmcnt(0)
	s_add_u32 s2, s2, s84
	s_addc_u32 s3, s3, 0
	s_add_u32 s17, s2, 0x200000
	s_addc_u32 s18, s3, 0
	s_ashr_i32 s5, s4, 31
	s_lshl_b64 s[2:3], s[4:5], 3
	s_add_u32 s2, s0, s2
	s_addc_u32 s3, s1, s3
	s_load_dwordx2 s[2:3], s[2:3], 0xd0
	v_mov_b32_e32 v143, v4
	s_waitcnt lgkmcnt(0)
	s_add_u32 s2, s2, s80
	s_addc_u32 s3, s3, 0
	s_lshl_b32 s4, s46, 19
	s_add_u32 s2, s2, s4
	s_addc_u32 s3, s3, 0
	v_readlane_b32 s4, v253, 62
	v_readlane_b32 s5, v253, 63
	s_add_u32 s2, s2, s4
	s_addc_u32 s3, s3, s5
	s_add_u32 s4, s2, 0xe00000
	s_addc_u32 s5, s3, 0
	s_ashr_i32 s7, s6, 31
	s_lshl_b64 s[2:3], s[6:7], 3
	s_add_u32 s2, s0, s2
	s_addc_u32 s3, s1, s3
	s_mov_b64 s[2:3], s[100:101]
	s_waitcnt lgkmcnt(0)
	s_add_u32 s2, s2, s81
	v_readfirstlane_b32 s6, v145
	s_addc_u32 s3, s3, 0
	s_ashr_i32 s9, s6, 6
	s_lshl_b32 s10, s9, 5
	s_lshl_b64 s[6:7], s[74:75], 8
	s_ashr_i32 s11, s10, 31
	s_add_u32 s19, s6, s10
	s_addc_u32 s20, s7, s11
	s_lshl_b32 s6, s78, 2
	s_ashr_i32 s7, s6, 31
	s_lshl_b64 s[10:11], s[6:7], 14
	s_add_u32 s10, s17, s10
	s_addc_u32 s11, s18, s11
	s_or_b32 s12, s6, 1
	s_ashr_i32 s13, s12, 31
	s_lshl_b64 s[12:13], s[12:13], 14
	s_add_u32 s12, s17, s12
	s_addc_u32 s13, s18, s13
	s_or_b32 s14, s6, 2
	s_ashr_i32 s15, s14, 31
	s_lshl_b64 s[14:15], s[14:15], 14
	s_add_u32 s14, s17, s14
	s_addc_u32 s15, s18, s15
	s_or_b32 s6, s6, 3
	v_and_b32_e32 v144, 15, v145
	s_ashr_i32 s7, s6, 31
	s_lshl_b64 s[6:7], s[6:7], 14
	v_or_b32_e32 v6, s19, v144
	s_add_u32 s6, s17, s6
	v_mov_b32_e32 v5, v6
	s_addc_u32 s7, s18, s7
	v_ashrrev_i64 v[2:3], 30, v[4:5]
	v_mov_b32_e32 v7, s20
	v_lshl_add_u64 v[8:9], s[10:11], 0, v[2:3]
	v_lshl_add_u64 v[10:11], s[12:13], 0, v[2:3]
	v_lshl_add_u64 v[12:13], s[14:15], 0, v[2:3]
	v_lshl_add_u64 v[2:3], s[6:7], 0, v[2:3]
	global_load_dword v14, v[8:9], off
	global_load_dword v16, v[10:11], off
	global_load_dword v15, v[12:13], off
	global_load_dword v17, v[2:3], off
	v_lshlrev_b64 v[2:3], 11, v[6:7]
	v_or_b32_e32 v6, 16, v6
	v_mov_b32_e32 v5, v6
	v_ashrrev_i64 v[8:9], 30, v[4:5]
	v_lshl_add_u64 v[10:11], s[10:11], 0, v[8:9]
	v_lshl_add_u64 v[12:13], s[12:13], 0, v[8:9]
	v_lshl_add_u64 v[18:19], s[14:15], 0, v[8:9]
	v_lshl_add_u64 v[8:9], s[6:7], 0, v[8:9]
	s_lshl_b32 s6, s78, 8
	s_ashr_i32 s7, s6, 31
	s_lshl_b64 s[6:7], s[6:7], 1
	s_add_u32 s10, s8, s6
	s_addc_u32 s11, s16, s7
	v_and_b32_e32 v142, 48, v145
	global_load_dword v20, v[10:11], off
	global_load_dword v22, v[12:13], off
	global_load_dword v21, v[18:19], off
	global_load_dword v23, v[8:9], off
	v_lshl_add_u64 v[8:9], s[10:11], 0, v[142:143]
	s_mov_b64 s[10:11], 0x9e00000
	v_lshl_add_u64 v[8:9], v[8:9], 0, s[10:11]
	v_lshlrev_b64 v[6:7], 11, v[6:7]
	v_lshl_add_u64 v[10:11], v[8:9], 0, v[2:3]
	v_lshl_add_u64 v[6:7], v[8:9], 0, v[6:7]
	global_load_dwordx4 v[66:69], v[10:11], off
	global_load_dwordx4 v[62:65], v[10:11], off offset:64
	global_load_dwordx4 v[58:61], v[10:11], off offset:128
	global_load_dwordx4 v[54:57], v[10:11], off offset:192
	global_load_dwordx4 v[50:53], v[10:11], off offset:256
	global_load_dwordx4 v[46:49], v[10:11], off offset:320
	global_load_dwordx4 v[42:45], v[10:11], off offset:384
	global_load_dwordx4 v[38:41], v[10:11], off offset:448
	global_load_dwordx4 v[98:101], v[6:7], off
	global_load_dwordx4 v[94:97], v[6:7], off offset:64
	global_load_dwordx4 v[90:93], v[6:7], off offset:128
	global_load_dwordx4 v[86:89], v[6:7], off offset:192
	global_load_dwordx4 v[82:85], v[6:7], off offset:256
	global_load_dwordx4 v[78:81], v[6:7], off offset:320
	global_load_dwordx4 v[74:77], v[6:7], off offset:384
	global_load_dwordx4 v[70:73], v[6:7], off offset:448
	v_bfe_u32 v5, v145, 4, 2
	v_bitop3_b32 v6, v5, v145, 15 bitop3:0x78
	v_bitop3_b32 v8, v5, v144, 8 bitop3:0x36
	v_bitop3_b32 v30, v5, v144, 24 bitop3:0x36
	v_lshl_add_u32 v134, v144, 9, 0
	v_bitop3_b32 v7, v5, v144, 4 bitop3:0x36
	v_bitop3_b32 v9, v5, v144, 12 bitop3:0x36
	v_lshlrev_b32_e32 v149, 4, v6
	v_lshlrev_b32_e32 v136, 4, v8
	v_lshlrev_b32_e32 v152, 4, v30
	v_lshlrev_b32_e32 v137, 4, v7
	v_lshlrev_b32_e32 v135, 4, v9
	v_add_u32_e32 v170, v134, v149
	v_add_u32_e32 v172, v134, v136
	v_add_u32_e32 v176, v134, v152
	v_add_u32_e32 v171, v134, v137
	v_add_u32_e32 v173, v134, v135
	s_waitcnt vmcnt(24)
	s_barrier
	ds_read_b128 v[6:9], v170
	ds_read_b128 v[10:13], v171
	v_lshrrev_b32_e32 v146, 1, v145
	s_lshl_b32 s8, s9, 3
	s_waitcnt vmcnt(20)
	v_pk_add_f32 v[14:15], v[14:15], v[16:17]
	s_nop 0
	v_add_f32_e32 v14, v14, v15
	v_fmamk_f32 v14, v14, 0x3b800000, v236
	v_rsq_f32_e32 v148, v14
	s_waitcnt vmcnt(16)
	v_pk_add_f32 v[16:17], v[20:21], v[22:23]
	v_bitop3_b32 v22, v5, v144, 16 bitop3:0x36
	v_lshlrev_b32_e32 v150, 4, v22
	v_bitop3_b32 v22, v5, v144, 20 bitop3:0x36
	v_bitop3_b32 v5, v5, v144, 28 bitop3:0x36
	v_add_f32_e32 v15, v16, v17
	v_add_u32_e32 v174, v134, v150
	v_lshlrev_b32_e32 v151, 4, v22
	v_lshlrev_b32_e32 v153, 4, v5
	v_fmamk_f32 v102, v15, 0x3b800000, v236
	ds_read_b128 v[14:17], v172
	ds_read_b128 v[18:21], v173
	v_add_u32_e32 v175, v134, v151
	ds_read_b128 v[22:25], v174
	ds_read_b128 v[26:29], v175
	v_add_u32_e32 v177, v134, v153
	ds_read_b128 v[30:33], v176
	ds_read_b128 v[34:37], v177
	v_rsq_f32_e32 v147, v102
	v_and_b32_e32 v5, 63, v145
	s_setprio 1
	s_waitcnt vmcnt(15) lgkmcnt(7)
	v_mfma_f32_16x16x32_bf16 v[102:105], v[6:9], v[66:69], 0
	s_waitcnt vmcnt(7)
	v_mfma_f32_16x16x32_bf16 v[6:9], v[6:9], v[98:101], 0
	s_waitcnt lgkmcnt(6)
	v_mfma_f32_16x16x32_bf16 v[102:105], v[10:13], v[62:65], v[102:105]
	s_waitcnt vmcnt(6)
	v_mfma_f32_16x16x32_bf16 v[6:9], v[10:13], v[94:97], v[6:9]
	s_waitcnt lgkmcnt(5)
	v_mfma_f32_16x16x32_bf16 v[10:13], v[14:17], v[58:61], v[102:105]
	s_waitcnt vmcnt(5)
	v_mfma_f32_16x16x32_bf16 v[6:9], v[14:17], v[90:93], v[6:9]
	s_waitcnt lgkmcnt(4)
	v_mfma_f32_16x16x32_bf16 v[10:13], v[18:21], v[54:57], v[10:13]
	s_waitcnt vmcnt(4)
	v_mfma_f32_16x16x32_bf16 v[6:9], v[18:21], v[86:89], v[6:9]
	s_setprio 0
	ds_read_b128 v[14:17], v170 offset:8192
	ds_read_b128 v[18:21], v171 offset:8192
	ds_read_b128 v[102:105], v172 offset:8192
	ds_read_b128 v[106:109], v173 offset:8192
	s_setprio 1
	s_waitcnt lgkmcnt(7)
	v_mfma_f32_16x16x32_bf16 v[10:13], v[22:25], v[50:53], v[10:13]
	s_waitcnt vmcnt(3)
	v_mfma_f32_16x16x32_bf16 v[6:9], v[22:25], v[82:85], v[6:9]
	s_waitcnt lgkmcnt(6)
	v_mfma_f32_16x16x32_bf16 v[10:13], v[26:29], v[46:49], v[10:13]
	s_waitcnt vmcnt(2)
	v_mfma_f32_16x16x32_bf16 v[6:9], v[26:29], v[78:81], v[6:9]
	s_waitcnt lgkmcnt(5)
	v_mfma_f32_16x16x32_bf16 v[10:13], v[30:33], v[42:45], v[10:13]
	s_waitcnt vmcnt(1)
	v_mfma_f32_16x16x32_bf16 v[6:9], v[30:33], v[74:77], v[6:9]
	s_waitcnt lgkmcnt(4)
	v_mfma_f32_16x16x32_bf16 v[10:13], v[34:37], v[38:41], v[10:13]
	s_waitcnt vmcnt(0)
	v_mfma_f32_16x16x32_bf16 v[22:25], v[34:37], v[70:73], v[6:9]
	s_setprio 0
	s_nop 2
	ds_read_b128 v[6:9], v174 offset:8192
	ds_read_b128 v[26:29], v175 offset:8192
	ds_read_b128 v[30:33], v176 offset:8192
	ds_read_b128 v[34:37], v177 offset:8192
	s_setprio 1
	s_waitcnt lgkmcnt(7)
	v_mfma_f32_16x16x32_bf16 v[110:113], v[14:17], v[66:69], 0
	v_mfma_f32_16x16x32_bf16 v[14:17], v[14:17], v[98:101], 0
	s_waitcnt lgkmcnt(6)
	v_mfma_f32_16x16x32_bf16 v[110:113], v[18:21], v[62:65], v[110:113]
	v_mfma_f32_16x16x32_bf16 v[14:17], v[18:21], v[94:97], v[14:17]
	s_waitcnt lgkmcnt(5)
	v_mfma_f32_16x16x32_bf16 v[18:21], v[102:105], v[58:61], v[110:113]
	v_mfma_f32_16x16x32_bf16 v[14:17], v[102:105], v[90:93], v[14:17]
	s_waitcnt lgkmcnt(4)
	v_mfma_f32_16x16x32_bf16 v[18:21], v[106:109], v[54:57], v[18:21]
	v_mfma_f32_16x16x32_bf16 v[14:17], v[106:109], v[86:89], v[14:17]
	s_setprio 0
	ds_read_b128 v[102:105], v170 offset:16384
	ds_read_b128 v[106:109], v171 offset:16384
	ds_read_b128 v[110:113], v172 offset:16384
	ds_read_b128 v[114:117], v173 offset:16384
	s_setprio 1
	s_waitcnt lgkmcnt(7)
	v_mfma_f32_16x16x32_bf16 v[18:21], v[6:9], v[50:53], v[18:21]
	v_mfma_f32_16x16x32_bf16 v[6:9], v[6:9], v[82:85], v[14:17]
	s_waitcnt lgkmcnt(6)
	v_mfma_f32_16x16x32_bf16 v[14:17], v[26:29], v[46:49], v[18:21]
	v_mfma_f32_16x16x32_bf16 v[6:9], v[26:29], v[78:81], v[6:9]
	s_waitcnt lgkmcnt(5)
	v_mfma_f32_16x16x32_bf16 v[14:17], v[30:33], v[42:45], v[14:17]
	v_mfma_f32_16x16x32_bf16 v[6:9], v[30:33], v[74:77], v[6:9]
	s_waitcnt lgkmcnt(4)
	v_mfma_f32_16x16x32_bf16 v[14:17], v[34:37], v[38:41], v[14:17]
	v_mfma_f32_16x16x32_bf16 v[26:29], v[34:37], v[70:73], v[6:9]
	s_setprio 0
	s_nop 3
	ds_read_b128 v[6:9], v174 offset:16384
	ds_read_b128 v[18:21], v175 offset:16384
	ds_read_b128 v[30:33], v176 offset:16384
	ds_read_b128 v[34:37], v177 offset:16384
	s_setprio 1
	s_waitcnt lgkmcnt(7)
	v_mfma_f32_16x16x32_bf16 v[118:121], v[102:105], v[66:69], 0
	v_mfma_f32_16x16x32_bf16 v[102:105], v[102:105], v[98:101], 0
	s_waitcnt lgkmcnt(6)
	v_mfma_f32_16x16x32_bf16 v[118:121], v[106:109], v[62:65], v[118:121]
	v_mfma_f32_16x16x32_bf16 v[102:105], v[106:109], v[94:97], v[102:105]
	s_waitcnt lgkmcnt(5)
	v_mfma_f32_16x16x32_bf16 v[106:109], v[110:113], v[58:61], v[118:121]
	v_mfma_f32_16x16x32_bf16 v[102:105], v[110:113], v[90:93], v[102:105]
	s_waitcnt lgkmcnt(4)
	v_mfma_f32_16x16x32_bf16 v[106:109], v[114:117], v[54:57], v[106:109]
	v_mfma_f32_16x16x32_bf16 v[102:105], v[114:117], v[86:89], v[102:105]
	s_setprio 0
	ds_read_b128 v[110:113], v170 offset:24576
	ds_read_b128 v[114:117], v171 offset:24576
	ds_read_b128 v[118:121], v172 offset:24576
	ds_read_b128 v[122:125], v173 offset:24576
	s_setprio 1
	s_waitcnt lgkmcnt(7)
	v_mfma_f32_16x16x32_bf16 v[106:109], v[6:9], v[50:53], v[106:109]
	v_mfma_f32_16x16x32_bf16 v[6:9], v[6:9], v[82:85], v[102:105]
	s_waitcnt lgkmcnt(6)
	v_mfma_f32_16x16x32_bf16 v[102:105], v[18:21], v[46:49], v[106:109]
	v_mfma_f32_16x16x32_bf16 v[6:9], v[18:21], v[78:81], v[6:9]
	s_waitcnt lgkmcnt(5)
	v_mfma_f32_16x16x32_bf16 v[18:21], v[30:33], v[42:45], v[102:105]
	v_mfma_f32_16x16x32_bf16 v[6:9], v[30:33], v[74:77], v[6:9]
	s_waitcnt lgkmcnt(4)
	v_mfma_f32_16x16x32_bf16 v[18:21], v[34:37], v[38:41], v[18:21]
	v_mfma_f32_16x16x32_bf16 v[30:33], v[34:37], v[70:73], v[6:9]
	s_setprio 0
	s_nop 3
	ds_read_b128 v[6:9], v174 offset:24576
	ds_read_b128 v[34:37], v175 offset:24576
	ds_read_b128 v[102:105], v176 offset:24576
	ds_read_b128 v[106:109], v177 offset:24576
	s_setprio 1
	s_waitcnt lgkmcnt(7)
	v_mfma_f32_16x16x32_bf16 v[126:129], v[110:113], v[66:69], 0
	v_mfma_f32_16x16x32_bf16 v[110:113], v[110:113], v[98:101], 0
	s_waitcnt lgkmcnt(6)
	v_mfma_f32_16x16x32_bf16 v[126:129], v[114:117], v[62:65], v[126:129]
	v_mfma_f32_16x16x32_bf16 v[110:113], v[114:117], v[94:97], v[110:113]
	s_waitcnt lgkmcnt(5)
	v_mfma_f32_16x16x32_bf16 v[114:117], v[118:121], v[58:61], v[126:129]
	v_mfma_f32_16x16x32_bf16 v[110:113], v[118:121], v[90:93], v[110:113]
	s_waitcnt lgkmcnt(4)
	v_mfma_f32_16x16x32_bf16 v[114:117], v[122:125], v[54:57], v[114:117]
	v_mfma_f32_16x16x32_bf16 v[110:113], v[122:125], v[86:89], v[110:113]
	s_setprio 0
	ds_read_b128 v[118:121], v170 offset:32768
	ds_read_b128 v[122:125], v171 offset:32768
	ds_read_b128 v[126:129], v172 offset:32768
	ds_read_b128 v[130:133], v173 offset:32768
	s_setprio 1
	s_waitcnt lgkmcnt(7)
	v_mfma_f32_16x16x32_bf16 v[114:117], v[6:9], v[50:53], v[114:117]
	v_mfma_f32_16x16x32_bf16 v[6:9], v[6:9], v[82:85], v[110:113]
	s_waitcnt lgkmcnt(6)
	v_mfma_f32_16x16x32_bf16 v[110:113], v[34:37], v[46:49], v[114:117]
	v_mfma_f32_16x16x32_bf16 v[6:9], v[34:37], v[78:81], v[6:9]
	s_waitcnt lgkmcnt(5)
	v_mfma_f32_16x16x32_bf16 v[34:37], v[102:105], v[42:45], v[110:113]
	v_mfma_f32_16x16x32_bf16 v[6:9], v[102:105], v[74:77], v[6:9]
	s_waitcnt lgkmcnt(4)
	v_mfma_f32_16x16x32_bf16 v[114:117], v[106:109], v[38:41], v[34:37]
	v_mfma_f32_16x16x32_bf16 v[34:37], v[106:109], v[70:73], v[6:9]
	s_setprio 0
	s_nop 3
	ds_read_b128 v[6:9], v174 offset:32768
	ds_read_b128 v[102:105], v175 offset:32768
	ds_read_b128 v[106:109], v176 offset:32768
	ds_read_b128 v[110:113], v177 offset:32768
	s_setprio 1
	s_waitcnt lgkmcnt(7)
	v_mfma_f32_16x16x32_bf16 v[138:141], v[118:121], v[66:69], 0
	v_mfma_f32_16x16x32_bf16 v[118:121], v[118:121], v[98:101], 0
	s_waitcnt lgkmcnt(6)
	v_mfma_f32_16x16x32_bf16 v[138:141], v[122:125], v[62:65], v[138:141]
	v_mfma_f32_16x16x32_bf16 v[118:121], v[122:125], v[94:97], v[118:121]
	s_waitcnt lgkmcnt(5)
	v_mfma_f32_16x16x32_bf16 v[122:125], v[126:129], v[58:61], v[138:141]
	v_mfma_f32_16x16x32_bf16 v[118:121], v[126:129], v[90:93], v[118:121]
	s_waitcnt lgkmcnt(4)
	v_mfma_f32_16x16x32_bf16 v[122:125], v[130:133], v[54:57], v[122:125]
	v_mfma_f32_16x16x32_bf16 v[118:121], v[130:133], v[86:89], v[118:121]
	s_setprio 0
	ds_read_b128 v[126:129], v170 offset:40960
	ds_read_b128 v[130:133], v171 offset:40960
	ds_read_b128 v[138:141], v172 offset:40960
	ds_read_b128 v[154:157], v173 offset:40960
	s_setprio 1
	s_waitcnt lgkmcnt(7)
	v_mfma_f32_16x16x32_bf16 v[122:125], v[6:9], v[50:53], v[122:125]
	v_mfma_f32_16x16x32_bf16 v[6:9], v[6:9], v[82:85], v[118:121]
	s_waitcnt lgkmcnt(6)
	v_mfma_f32_16x16x32_bf16 v[118:121], v[102:105], v[46:49], v[122:125]
	v_mfma_f32_16x16x32_bf16 v[6:9], v[102:105], v[78:81], v[6:9]
	s_waitcnt lgkmcnt(5)
	v_mfma_f32_16x16x32_bf16 v[102:105], v[106:109], v[42:45], v[118:121]
	v_mfma_f32_16x16x32_bf16 v[6:9], v[106:109], v[74:77], v[6:9]
	s_waitcnt lgkmcnt(4)
	v_mfma_f32_16x16x32_bf16 v[118:121], v[110:113], v[38:41], v[102:105]
	v_mfma_f32_16x16x32_bf16 v[102:105], v[110:113], v[70:73], v[6:9]
	s_setprio 0
	s_nop 3
	ds_read_b128 v[6:9], v174 offset:40960
	ds_read_b128 v[106:109], v175 offset:40960
	ds_read_b128 v[110:113], v176 offset:40960
	ds_read_b128 v[122:125], v177 offset:40960
	s_setprio 1
	s_waitcnt lgkmcnt(7)
	v_mfma_f32_16x16x32_bf16 v[158:161], v[126:129], v[66:69], 0
	v_mfma_f32_16x16x32_bf16 v[126:129], v[126:129], v[98:101], 0
	s_waitcnt lgkmcnt(6)
	v_mfma_f32_16x16x32_bf16 v[158:161], v[130:133], v[62:65], v[158:161]
	v_mfma_f32_16x16x32_bf16 v[126:129], v[130:133], v[94:97], v[126:129]
	s_waitcnt lgkmcnt(5)
	v_mfma_f32_16x16x32_bf16 v[130:133], v[138:141], v[58:61], v[158:161]
	v_mfma_f32_16x16x32_bf16 v[126:129], v[138:141], v[90:93], v[126:129]
	s_waitcnt lgkmcnt(4)
	v_mfma_f32_16x16x32_bf16 v[130:133], v[154:157], v[54:57], v[130:133]
	v_mfma_f32_16x16x32_bf16 v[126:129], v[154:157], v[86:89], v[126:129]
	s_setprio 0
	ds_read_b128 v[138:141], v170 offset:49152
	ds_read_b128 v[154:157], v171 offset:49152
	ds_read_b128 v[158:161], v172 offset:49152
	ds_read_b128 v[162:165], v173 offset:49152
	s_setprio 1
	s_waitcnt lgkmcnt(7)
	v_mfma_f32_16x16x32_bf16 v[130:133], v[6:9], v[50:53], v[130:133]
	v_mfma_f32_16x16x32_bf16 v[6:9], v[6:9], v[82:85], v[126:129]
	s_waitcnt lgkmcnt(6)
	v_mfma_f32_16x16x32_bf16 v[126:129], v[106:109], v[46:49], v[130:133]
	v_mfma_f32_16x16x32_bf16 v[6:9], v[106:109], v[78:81], v[6:9]
	s_waitcnt lgkmcnt(5)
	v_mfma_f32_16x16x32_bf16 v[106:109], v[110:113], v[42:45], v[126:129]
	v_mfma_f32_16x16x32_bf16 v[6:9], v[110:113], v[74:77], v[6:9]
	s_waitcnt lgkmcnt(4)
	v_mfma_f32_16x16x32_bf16 v[126:129], v[122:125], v[38:41], v[106:109]
	v_mfma_f32_16x16x32_bf16 v[106:109], v[122:125], v[70:73], v[6:9]
	s_setprio 0
	s_nop 3
	ds_read_b128 v[6:9], v174 offset:49152
	ds_read_b128 v[110:113], v175 offset:49152
	ds_read_b128 v[122:125], v176 offset:49152
	ds_read_b128 v[130:133], v177 offset:49152
	s_setprio 1
	s_waitcnt lgkmcnt(7)
	v_mfma_f32_16x16x32_bf16 v[166:169], v[138:141], v[66:69], 0
	v_mfma_f32_16x16x32_bf16 v[138:141], v[138:141], v[98:101], 0
	s_waitcnt lgkmcnt(6)
	v_mfma_f32_16x16x32_bf16 v[166:169], v[154:157], v[62:65], v[166:169]
	v_mfma_f32_16x16x32_bf16 v[138:141], v[154:157], v[94:97], v[138:141]
	s_waitcnt lgkmcnt(5)
	v_mfma_f32_16x16x32_bf16 v[154:157], v[158:161], v[58:61], v[166:169]
	v_mfma_f32_16x16x32_bf16 v[138:141], v[158:161], v[90:93], v[138:141]
	s_waitcnt lgkmcnt(4)
	v_mfma_f32_16x16x32_bf16 v[154:157], v[162:165], v[54:57], v[154:157]
	v_mfma_f32_16x16x32_bf16 v[138:141], v[162:165], v[86:89], v[138:141]
	s_setprio 0
	ds_read_b128 v[158:161], v170 offset:57344
	ds_read_b128 v[162:165], v171 offset:57344
	ds_read_b128 v[166:169], v172 offset:57344
	ds_read_b128 v[170:173], v173 offset:57344
	s_setprio 1
	s_waitcnt lgkmcnt(7)
	v_mfma_f32_16x16x32_bf16 v[154:157], v[6:9], v[50:53], v[154:157]
	v_mfma_f32_16x16x32_bf16 v[6:9], v[6:9], v[82:85], v[138:141]
	s_waitcnt lgkmcnt(6)
	v_mfma_f32_16x16x32_bf16 v[138:141], v[110:113], v[46:49], v[154:157]
	v_mfma_f32_16x16x32_bf16 v[6:9], v[110:113], v[78:81], v[6:9]
	s_waitcnt lgkmcnt(5)
	v_mfma_f32_16x16x32_bf16 v[110:113], v[122:125], v[42:45], v[138:141]
	v_mfma_f32_16x16x32_bf16 v[6:9], v[122:125], v[74:77], v[6:9]
	s_waitcnt lgkmcnt(4)
	v_mfma_f32_16x16x32_bf16 v[122:125], v[130:133], v[38:41], v[110:113]
	v_mfma_f32_16x16x32_bf16 v[110:113], v[130:133], v[70:73], v[6:9]
	s_setprio 0
	s_nop 3
	ds_read_b128 v[6:9], v174 offset:57344
	ds_read_b128 v[130:133], v175 offset:57344
	ds_read_b128 v[138:141], v176 offset:57344
	ds_read_b128 v[154:157], v177 offset:57344
	s_setprio 1
	s_waitcnt lgkmcnt(7)
	v_mfma_f32_16x16x32_bf16 v[174:177], v[158:161], v[66:69], 0
	v_mfma_f32_16x16x32_bf16 v[158:161], v[158:161], v[98:101], 0
	s_waitcnt lgkmcnt(6)
	v_mfma_f32_16x16x32_bf16 v[174:177], v[162:165], v[62:65], v[174:177]
	v_mfma_f32_16x16x32_bf16 v[158:161], v[162:165], v[94:97], v[158:161]
	s_waitcnt lgkmcnt(5)
	v_mfma_f32_16x16x32_bf16 v[162:165], v[166:169], v[58:61], v[174:177]
	v_mfma_f32_16x16x32_bf16 v[158:161], v[166:169], v[90:93], v[158:161]
	s_waitcnt lgkmcnt(4)
	v_mfma_f32_16x16x32_bf16 v[162:165], v[170:173], v[54:57], v[162:165]
	v_mfma_f32_16x16x32_bf16 v[158:161], v[170:173], v[86:89], v[158:161]
	s_setprio 0
	s_setprio 1
	s_waitcnt lgkmcnt(3)
	v_mfma_f32_16x16x32_bf16 v[162:165], v[6:9], v[50:53], v[162:165]
	v_mfma_f32_16x16x32_bf16 v[6:9], v[6:9], v[82:85], v[158:161]
	s_waitcnt lgkmcnt(2)
	v_mfma_f32_16x16x32_bf16 v[158:161], v[130:133], v[46:49], v[162:165]
	v_mfma_f32_16x16x32_bf16 v[6:9], v[130:133], v[78:81], v[6:9]
	s_waitcnt lgkmcnt(1)
	v_mfma_f32_16x16x32_bf16 v[130:133], v[138:141], v[42:45], v[158:161]
	v_mfma_f32_16x16x32_bf16 v[6:9], v[138:141], v[74:77], v[6:9]
	s_waitcnt lgkmcnt(0)
	v_mfma_f32_16x16x32_bf16 v[130:133], v[154:157], v[38:41], v[130:133]
	v_mfma_f32_16x16x32_bf16 v[138:141], v[154:157], v[70:73], v[6:9]
	s_setprio 0
	s_nop 3
	v_mul_f32_e32 v7, v148, v14
	v_mul_f32_e32 v6, v148, v10
	v_exp_f32_e32 v8, v7
	v_mul_f32_e32 v7, v148, v11
	v_mul_f32_e32 v10, v148, v12
	v_mul_f32_e32 v12, v148, v13
	v_exp_f32_e32 v6, v6
	v_exp_f32_e32 v7, v7
	v_mul_f32_e32 v9, v148, v15
	v_exp_f32_e32 v10, v10
	v_mul_f32_e32 v11, v148, v16
	v_exp_f32_e32 v12, v12
	v_mul_f32_e32 v13, v148, v17
	v_exp_f32_e32 v9, v9
	v_exp_f32_e32 v11, v11
	v_exp_f32_e32 v13, v13
	v_add_f32_e32 v14, v6, v7
	v_add_f32_e32 v15, v10, v12
	v_add_f32_e32 v14, v14, v15
	v_add_f32_e32 v15, v8, v9
	v_add_f32_e32 v16, v11, v13
	v_add_f32_e32 v15, v15, v16
	v_cvt_pk_bf16_f32 v8, v8, v9
	v_cvt_pk_bf16_f32 v9, v11, v13
	v_mul_f32_e32 v11, v148, v114
	v_add_f32_e32 v14, v14, v15
	v_cvt_pk_bf16_f32 v6, v6, v7
	v_cvt_pk_bf16_f32 v7, v10, v12
	v_mul_f32_e32 v10, v148, v18
	v_exp_f32_e32 v12, v11
	v_mul_f32_e32 v11, v148, v19
	v_mul_f32_e32 v15, v148, v20
	v_mul_f32_e32 v17, v148, v21
	v_exp_f32_e32 v10, v10
	v_exp_f32_e32 v11, v11
	v_mul_f32_e32 v13, v148, v115
	v_exp_f32_e32 v15, v15
	v_mul_f32_e32 v16, v148, v116
	v_exp_f32_e32 v17, v17
	v_mul_f32_e32 v18, v148, v117
	v_exp_f32_e32 v13, v13
	v_exp_f32_e32 v16, v16
	v_exp_f32_e32 v18, v18
	v_add_f32_e32 v19, v10, v11
	v_add_f32_e32 v20, v15, v17
	v_add_f32_e32 v19, v19, v20
	v_add_f32_e32 v20, v12, v13
	v_add_f32_e32 v21, v16, v18
	v_add_f32_e32 v20, v20, v21
	v_add_f32_e32 v14, 0, v14
	v_add_f32_e32 v19, v19, v20
	v_add_f32_e32 v14, v14, v19
	v_cvt_pk_bf16_f32 v10, v10, v11
	v_cvt_pk_bf16_f32 v11, v15, v17
	v_mul_f32_e32 v15, v148, v118
	v_mul_f32_e32 v17, v148, v119
	v_mul_f32_e32 v19, v148, v120
	v_mul_f32_e32 v21, v148, v121
	v_cvt_pk_bf16_f32 v12, v12, v13
	v_cvt_pk_bf16_f32 v13, v16, v18
	v_exp_f32_e32 v15, v15
	v_mul_f32_e32 v16, v148, v126
	v_exp_f32_e32 v17, v17
	v_mul_f32_e32 v18, v148, v127
	v_exp_f32_e32 v19, v19
	v_mul_f32_e32 v20, v148, v128
	v_exp_f32_e32 v21, v21
	v_mul_f32_e32 v114, v148, v129
	v_exp_f32_e32 v16, v16
	v_exp_f32_e32 v18, v18
	v_exp_f32_e32 v20, v20
	v_exp_f32_e32 v114, v114
	v_add_f32_e32 v115, v15, v17
	v_add_f32_e32 v116, v19, v21
	v_add_f32_e32 v115, v115, v116
	v_add_f32_e32 v116, v16, v18
	v_add_f32_e32 v117, v20, v114
	v_add_f32_e32 v116, v116, v117
	v_add_f32_e32 v115, v115, v116
	v_add_f32_e32 v115, v14, v115
	v_cvt_pk_bf16_f32 v14, v15, v17
	v_cvt_pk_bf16_f32 v15, v19, v21
	v_mul_f32_e32 v19, v148, v130
	v_cvt_pk_bf16_f32 v16, v16, v18
	v_cvt_pk_bf16_f32 v17, v20, v114
	v_mul_f32_e32 v18, v148, v122
	v_exp_f32_e32 v20, v19
	v_mul_f32_e32 v19, v148, v123
	v_mul_f32_e32 v114, v148, v124
	v_mul_f32_e32 v117, v148, v125
	v_exp_f32_e32 v18, v18
	v_exp_f32_e32 v19, v19
	v_mul_f32_e32 v21, v148, v131
	v_exp_f32_e32 v114, v114
	v_mul_f32_e32 v116, v148, v132
	v_exp_f32_e32 v117, v117
	v_mul_f32_e32 v118, v148, v133
	v_exp_f32_e32 v21, v21
	v_exp_f32_e32 v116, v116
	v_exp_f32_e32 v118, v118
	v_mul_f32_e32 v22, v147, v22
	v_mul_f32_e32 v23, v147, v23
	v_mul_f32_e32 v24, v147, v24
	v_mul_f32_e32 v25, v147, v25
	v_add_f32_e32 v119, v18, v19
	v_add_f32_e32 v120, v114, v117
	v_exp_f32_e32 v22, v22
	v_mul_f32_e32 v26, v147, v26
	v_exp_f32_e32 v23, v23
	v_mul_f32_e32 v27, v147, v27
	v_exp_f32_e32 v24, v24
	v_exp_f32_e32 v25, v25
	v_add_f32_e32 v119, v119, v120
	v_add_f32_e32 v120, v20, v21
	v_add_f32_e32 v121, v116, v118
	v_exp_f32_e32 v26, v26
	v_exp_f32_e32 v27, v27
	v_mul_f32_e32 v28, v147, v28
	v_mul_f32_e32 v29, v147, v29
	v_add_f32_e32 v120, v120, v121
	v_exp_f32_e32 v28, v28
	v_exp_f32_e32 v29, v29
	v_add_f32_e32 v119, v119, v120
	v_add_f32_e32 v155, v115, v119
	v_cvt_pk_bf16_f32 v18, v18, v19
	v_cvt_pk_bf16_f32 v19, v114, v117
	v_add_f32_e32 v114, v22, v23
	v_add_f32_e32 v115, v24, v25
	v_add_f32_e32 v114, v114, v115
	v_add_f32_e32 v115, v26, v27
	v_cvt_pk_bf16_f32 v22, v22, v23
	v_cvt_pk_bf16_f32 v23, v24, v25
	v_cvt_pk_bf16_f32 v24, v26, v27
	v_mul_f32_e32 v27, v147, v34
	v_cvt_pk_bf16_f32 v20, v20, v21
	v_cvt_pk_bf16_f32 v21, v116, v118
	v_add_f32_e32 v116, v28, v29
	v_cvt_pk_bf16_f32 v25, v28, v29
	v_mul_f32_e32 v26, v147, v30
	v_exp_f32_e32 v28, v27
	v_mul_f32_e32 v27, v147, v31
	v_mul_f32_e32 v30, v147, v32
	v_mul_f32_e32 v32, v147, v33
	v_exp_f32_e32 v26, v26
	v_exp_f32_e32 v27, v27
	v_mul_f32_e32 v29, v147, v35
	v_exp_f32_e32 v30, v30
	v_mul_f32_e32 v31, v147, v36
	v_exp_f32_e32 v32, v32
	v_mul_f32_e32 v33, v147, v37
	v_exp_f32_e32 v29, v29
	v_exp_f32_e32 v31, v31
	v_exp_f32_e32 v33, v33
	v_add_f32_e32 v34, v26, v27
	v_add_f32_e32 v35, v30, v32
	v_add_f32_e32 v34, v34, v35
	v_add_f32_e32 v35, v28, v29
	v_add_f32_e32 v36, v31, v33
	v_add_f32_e32 v35, v35, v36
	v_cvt_pk_bf16_f32 v28, v28, v29
	v_cvt_pk_bf16_f32 v29, v31, v33
	v_mul_f32_e32 v31, v147, v106
	v_add_f32_e32 v34, v34, v35
	v_cvt_pk_bf16_f32 v26, v26, v27
	v_cvt_pk_bf16_f32 v27, v30, v32
	v_mul_f32_e32 v30, v147, v102
	v_exp_f32_e32 v32, v31
	v_mul_f32_e32 v31, v147, v103
	v_mul_f32_e32 v35, v147, v104
	v_mul_f32_e32 v37, v147, v105
	v_exp_f32_e32 v30, v30
	v_exp_f32_e32 v31, v31
	v_mul_f32_e32 v33, v147, v107
	v_exp_f32_e32 v35, v35
	v_mul_f32_e32 v36, v147, v108
	v_exp_f32_e32 v37, v37
	v_mul_f32_e32 v102, v147, v109
	v_exp_f32_e32 v33, v33
	v_exp_f32_e32 v36, v36
	v_exp_f32_e32 v102, v102
	v_add_f32_e32 v115, v115, v116
	v_add_f32_e32 v103, v30, v31
	v_add_f32_e32 v104, v35, v37
	v_add_f32_e32 v114, v114, v115
	v_add_f32_e32 v103, v103, v104
	v_add_f32_e32 v104, v32, v33
	v_add_f32_e32 v105, v36, v102
	v_add_f32_e32 v114, 0, v114
	v_add_f32_e32 v104, v104, v105
	v_add_f32_e32 v34, v114, v34
	v_add_f32_e32 v103, v103, v104
	v_add_f32_e32 v34, v34, v103
	v_cvt_pk_bf16_f32 v30, v30, v31
	v_cvt_pk_bf16_f32 v31, v35, v37
	v_mul_f32_e32 v35, v147, v110
	v_mul_f32_e32 v37, v147, v111
	v_mul_f32_e32 v103, v147, v112
	v_mul_f32_e32 v105, v147, v113
	v_cvt_pk_bf16_f32 v32, v32, v33
	v_cvt_pk_bf16_f32 v33, v36, v102
	v_exp_f32_e32 v35, v35
	v_mul_f32_e32 v36, v147, v138
	v_exp_f32_e32 v37, v37
	v_mul_f32_e32 v102, v147, v139
	v_exp_f32_e32 v103, v103
	v_mul_f32_e32 v104, v147, v140
	v_exp_f32_e32 v105, v105
	v_mul_f32_e32 v106, v147, v141
	v_exp_f32_e32 v36, v36
	v_exp_f32_e32 v102, v102
	v_exp_f32_e32 v104, v104
	v_exp_f32_e32 v106, v106
	v_add_f32_e32 v107, v35, v37
	v_add_f32_e32 v108, v103, v105
	v_add_f32_e32 v107, v107, v108
	v_add_f32_e32 v108, v36, v102
	v_add_f32_e32 v109, v104, v106
	v_add_f32_e32 v108, v108, v109
	v_add_f32_e32 v107, v107, v108
	v_cvt_pk_bf16_f32 v36, v36, v102
	v_mov_b32_e32 v102, v5
	v_add_f32_e32 v154, v34, v107
	v_cvt_pk_bf16_f32 v34, v35, v37
	v_cvt_pk_bf16_f32 v37, v104, v106
	s_barrier
	v_cvt_pk_bf16_f32 v35, v103, v105
	v_mov_b32_e32 v105, v4
	v_ashrrev_i32_e32 v106, 5, v102
	v_and_b32_e32 v107, 31, v102
	v_lshl_add_u32 v102, s9, 4, v106
	v_lshrrev_b32_e32 v103, 1, v102
	v_and_b32_e32 v103, 12, v103
	v_and_b32_e32 v108, 3, v106
	v_bitop3_b32 v104, v103, v107, v108 bitop3:0x36
	v_ashrrev_i32_e32 v103, 31, v102
	v_lshlrev_b64 v[102:103], 9, v[102:103]
	v_lshl_add_u64 v[102:103], s[4:5], 0, v[102:103]
	v_lshlrev_b32_e32 v104, 4, v104
	s_lshl_b32 s9, s9, 13
	v_lshl_add_u64 v[102:103], v[102:103], 0, v[104:105]
	s_add_i32 m0, s9, 0
	s_or_b32 s9, s8, 1
	global_load_lds_dwordx4 v[102:103], off
	v_lshl_add_u32 v102, s9, 1, v106
	v_lshrrev_b32_e32 v103, 1, v102
	v_and_b32_e32 v103, 12, v103
	v_and_b32_e32 v104, 3, v102
	v_bitop3_b32 v104, v103, v107, v104 bitop3:0x36
	v_ashrrev_i32_e32 v103, 31, v102
	v_lshlrev_b64 v[102:103], 9, v[102:103]
	v_lshl_add_u64 v[102:103], s[4:5], 0, v[102:103]
	v_lshlrev_b32_e32 v104, 4, v104
	s_lshl_b32 s9, s9, 10
	v_lshl_add_u64 v[102:103], v[102:103], 0, v[104:105]
	s_add_i32 m0, s9, 0
	s_or_b32 s9, s8, 2
	global_load_lds_dwordx4 v[102:103], off
	v_lshl_add_u32 v102, s9, 1, v106
	v_lshrrev_b32_e32 v103, 1, v102
	v_and_b32_e32 v103, 12, v103
	v_bitop3_b32 v104, v103, v107, v108 bitop3:0x36
	v_ashrrev_i32_e32 v103, 31, v102
	v_lshlrev_b64 v[102:103], 9, v[102:103]
	v_lshl_add_u64 v[102:103], s[4:5], 0, v[102:103]
	v_lshlrev_b32_e32 v104, 4, v104
	s_lshl_b32 s9, s9, 10
	v_lshl_add_u64 v[102:103], v[102:103], 0, v[104:105]
	s_add_i32 m0, s9, 0
	s_or_b32 s9, s8, 3
	global_load_lds_dwordx4 v[102:103], off
	v_lshl_add_u32 v102, s9, 1, v106
	v_lshrrev_b32_e32 v103, 1, v102
	v_and_b32_e32 v103, 12, v103
	v_and_b32_e32 v104, 3, v102
	v_bitop3_b32 v104, v103, v107, v104 bitop3:0x36
	v_ashrrev_i32_e32 v103, 31, v102
	v_lshlrev_b64 v[102:103], 9, v[102:103]
	v_lshl_add_u64 v[102:103], s[4:5], 0, v[102:103]
	v_lshlrev_b32_e32 v104, 4, v104
	s_lshl_b32 s9, s9, 10
	v_lshl_add_u64 v[102:103], v[102:103], 0, v[104:105]
	s_add_i32 m0, s9, 0
	s_or_b32 s9, s8, 4
	global_load_lds_dwordx4 v[102:103], off
	v_lshl_add_u32 v102, s9, 1, v106
	v_lshrrev_b32_e32 v103, 1, v102
	v_and_b32_e32 v103, 12, v103
	v_bitop3_b32 v104, v103, v107, v108 bitop3:0x36
	v_ashrrev_i32_e32 v103, 31, v102
	v_lshlrev_b64 v[102:103], 9, v[102:103]
	v_lshl_add_u64 v[102:103], s[4:5], 0, v[102:103]
	v_lshlrev_b32_e32 v104, 4, v104
	s_lshl_b32 s9, s9, 10
	v_lshl_add_u64 v[102:103], v[102:103], 0, v[104:105]
	s_add_i32 m0, s9, 0
	s_or_b32 s9, s8, 5
	global_load_lds_dwordx4 v[102:103], off
	v_lshl_add_u32 v102, s9, 1, v106
	v_lshrrev_b32_e32 v103, 1, v102
	v_and_b32_e32 v103, 12, v103
	v_and_b32_e32 v104, 3, v102
	v_bitop3_b32 v104, v103, v107, v104 bitop3:0x36
	v_ashrrev_i32_e32 v103, 31, v102
	v_lshlrev_b64 v[102:103], 9, v[102:103]
	v_lshl_add_u64 v[102:103], s[4:5], 0, v[102:103]
	v_lshlrev_b32_e32 v104, 4, v104
	s_lshl_b32 s9, s9, 10
	v_lshl_add_u64 v[102:103], v[102:103], 0, v[104:105]
	s_add_i32 m0, s9, 0
	s_or_b32 s9, s8, 6
	global_load_lds_dwordx4 v[102:103], off
	v_lshl_add_u32 v102, s9, 1, v106
	v_lshrrev_b32_e32 v103, 1, v102
	v_and_b32_e32 v103, 12, v103
	v_bitop3_b32 v104, v103, v107, v108 bitop3:0x36
	v_ashrrev_i32_e32 v103, 31, v102
	v_lshlrev_b64 v[102:103], 9, v[102:103]
	v_lshl_add_u64 v[102:103], s[4:5], 0, v[102:103]
	v_lshlrev_b32_e32 v104, 4, v104
	s_lshl_b32 s9, s9, 10
	v_lshl_add_u64 v[102:103], v[102:103], 0, v[104:105]
	s_add_i32 m0, s9, 0
	s_or_b32 s9, s8, 7
	global_load_lds_dwordx4 v[102:103], off
	v_lshl_add_u32 v102, s9, 1, v106
	v_lshrrev_b32_e32 v103, 1, v102
	v_and_b32_e32 v103, 12, v103
	v_and_b32_e32 v104, 3, v102
	v_bitop3_b32 v104, v103, v107, v104 bitop3:0x36
	v_ashrrev_i32_e32 v103, 31, v102
	v_lshlrev_b64 v[102:103], 9, v[102:103]
	v_lshl_add_u64 v[102:103], s[4:5], 0, v[102:103]
	v_lshlrev_b32_e32 v104, 4, v104
	s_lshl_b32 s9, s9, 10
	v_lshl_add_u64 v[102:103], v[102:103], 0, v[104:105]
	s_add_i32 m0, s9, 0
	v_add_u32_e32 v130, 0x10000, v134
	global_load_lds_dwordx4 v[102:103], off
	v_add_u32_e32 v102, v130, v149
	v_add_u32_e32 v106, v130, v137
	v_add_u32_e32 v110, v130, v136
	v_add_u32_e32 v114, v130, v135
	v_add_u32_e32 v118, v130, v150
	v_add_u32_e32 v122, v130, v151
	v_add_u32_e32 v126, v130, v152
	v_add_u32_e32 v130, v130, v153
	ds_read_b128 v[102:105], v102
	ds_read_b128 v[106:109], v106
	ds_read_b128 v[110:113], v110
	ds_read_b128 v[114:117], v114
	ds_read_b128 v[118:121], v118
	ds_read_b128 v[122:125], v122
	ds_read_b128 v[126:129], v126
	ds_read_b128 v[130:133], v130
	s_setprio 1
	s_waitcnt lgkmcnt(0)
	v_mfma_f32_16x16x32_bf16 v[138:141], v[102:105], v[66:69], 0
	v_mfma_f32_16x16x32_bf16 v[102:105], v[102:105], v[98:101], 0
	v_mfma_f32_16x16x32_bf16 v[138:141], v[106:109], v[62:65], v[138:141]
	v_mfma_f32_16x16x32_bf16 v[102:105], v[106:109], v[94:97], v[102:105]
	v_mfma_f32_16x16x32_bf16 v[106:109], v[110:113], v[58:61], v[138:141]
	v_mfma_f32_16x16x32_bf16 v[102:105], v[110:113], v[90:93], v[102:105]
	v_mfma_f32_16x16x32_bf16 v[106:109], v[114:117], v[54:57], v[106:109]
	v_mfma_f32_16x16x32_bf16 v[102:105], v[114:117], v[86:89], v[102:105]
	s_setprio 0
	v_add_u32_e32 v160, 0x12000, v134
	v_add_u32_e32 v110, v160, v149
	v_add_u32_e32 v114, v160, v137
	v_add_u32_e32 v138, v160, v136
	v_add_u32_e32 v156, v160, v135
	ds_read_b128 v[110:113], v110
	ds_read_b128 v[114:117], v114
	ds_read_b128 v[138:141], v138
	ds_read_b128 v[156:159], v156
	s_setprio 1
	v_mfma_f32_16x16x32_bf16 v[106:109], v[118:121], v[50:53], v[106:109]
	v_mfma_f32_16x16x32_bf16 v[102:105], v[118:121], v[82:85], v[102:105]
	v_mfma_f32_16x16x32_bf16 v[106:109], v[122:125], v[46:49], v[106:109]
	v_mfma_f32_16x16x32_bf16 v[102:105], v[122:125], v[78:81], v[102:105]
	v_mfma_f32_16x16x32_bf16 v[106:109], v[126:129], v[42:45], v[106:109]
	v_mfma_f32_16x16x32_bf16 v[102:105], v[126:129], v[74:77], v[102:105]
	v_mfma_f32_16x16x32_bf16 v[122:125], v[130:133], v[38:41], v[106:109]
	v_mfma_f32_16x16x32_bf16 v[102:105], v[130:133], v[70:73], v[102:105]
	s_setprio 0
	s_nop 3
	v_add_u32_e32 v106, v160, v150
	v_add_u32_e32 v118, v160, v151
	v_add_u32_e32 v126, v160, v152
	ds_read_b128 v[106:109], v106
	ds_read_b128 v[118:121], v118
	v_add_u32_e32 v130, v160, v153
	ds_read_b128 v[126:129], v126
	ds_read_b128 v[160:163], v130
	s_setprio 1
	s_waitcnt lgkmcnt(0)
	v_mfma_f32_16x16x32_bf16 v[130:133], v[110:113], v[66:69], 0
	v_mfma_f32_16x16x32_bf16 v[110:113], v[110:113], v[98:101], 0
	v_mfma_f32_16x16x32_bf16 v[130:133], v[114:117], v[62:65], v[130:133]
	v_mfma_f32_16x16x32_bf16 v[110:113], v[114:117], v[94:97], v[110:113]
	v_mfma_f32_16x16x32_bf16 v[114:117], v[138:141], v[58:61], v[130:133]
	v_mfma_f32_16x16x32_bf16 v[110:113], v[138:141], v[90:93], v[110:113]
	v_mfma_f32_16x16x32_bf16 v[114:117], v[156:159], v[54:57], v[114:117]
	v_mfma_f32_16x16x32_bf16 v[110:113], v[156:159], v[86:89], v[110:113]
	s_setprio 0
	v_add_u32_e32 v172, 0x14000, v134
	s_nop 0
	v_add_u32_e32 v130, v172, v149
	v_add_u32_e32 v131, v172, v137
	ds_read_b128 v[138:141], v130
	ds_read_b128 v[156:159], v131
	v_add_u32_e32 v130, v172, v136
	v_add_u32_e32 v131, v172, v135
	ds_read_b128 v[164:167], v130
	ds_read_b128 v[168:171], v131
	s_setprio 1
	v_mfma_f32_16x16x32_bf16 v[114:117], v[106:109], v[50:53], v[114:117]
	v_mfma_f32_16x16x32_bf16 v[106:109], v[106:109], v[82:85], v[110:113]
	v_mfma_f32_16x16x32_bf16 v[110:113], v[118:121], v[46:49], v[114:117]
	v_mfma_f32_16x16x32_bf16 v[106:109], v[118:121], v[78:81], v[106:109]
	v_mfma_f32_16x16x32_bf16 v[110:113], v[126:129], v[42:45], v[110:113]
	v_mfma_f32_16x16x32_bf16 v[106:109], v[126:129], v[74:77], v[106:109]
	v_mfma_f32_16x16x32_bf16 v[130:133], v[160:163], v[38:41], v[110:113]
	v_mfma_f32_16x16x32_bf16 v[106:109], v[160:163], v[70:73], v[106:109]
	s_setprio 0
	s_nop 3
	v_add_u32_e32 v110, v172, v150
	v_add_u32_e32 v114, v172, v151
	v_add_u32_e32 v118, v172, v152
	v_add_u32_e32 v126, v172, v153
	ds_read_b128 v[110:113], v110
	ds_read_b128 v[114:117], v114
	ds_read_b128 v[118:121], v118
	ds_read_b128 v[126:129], v126
	s_setprio 1
	s_waitcnt lgkmcnt(0)
	v_mfma_f32_16x16x32_bf16 v[160:163], v[138:141], v[66:69], 0
	v_mfma_f32_16x16x32_bf16 v[138:141], v[138:141], v[98:101], 0
	v_mfma_f32_16x16x32_bf16 v[160:163], v[156:159], v[62:65], v[160:163]
	v_mfma_f32_16x16x32_bf16 v[138:141], v[156:159], v[94:97], v[138:141]
	v_mfma_f32_16x16x32_bf16 v[156:159], v[164:167], v[58:61], v[160:163]
	v_mfma_f32_16x16x32_bf16 v[138:141], v[164:167], v[90:93], v[138:141]
	v_mfma_f32_16x16x32_bf16 v[156:159], v[168:171], v[54:57], v[156:159]
	v_mfma_f32_16x16x32_bf16 v[138:141], v[168:171], v[86:89], v[138:141]
	s_setprio 0
	v_add_u32_e32 v176, 0x16000, v134
	s_nop 0
	v_add_u32_e32 v160, v176, v149
	v_add_u32_e32 v164, v176, v137
	v_add_u32_e32 v168, v176, v136
	v_add_u32_e32 v172, v176, v135
	ds_read_b128 v[160:163], v160
	ds_read_b128 v[164:167], v164
	ds_read_b128 v[168:171], v168
	ds_read_b128 v[172:175], v172
	s_setprio 1
	v_mfma_f32_16x16x32_bf16 v[156:159], v[110:113], v[50:53], v[156:159]
	v_mfma_f32_16x16x32_bf16 v[110:113], v[110:113], v[82:85], v[138:141]
	v_mfma_f32_16x16x32_bf16 v[138:141], v[114:117], v[46:49], v[156:159]
	v_mfma_f32_16x16x32_bf16 v[110:113], v[114:117], v[78:81], v[110:113]
	v_mfma_f32_16x16x32_bf16 v[114:117], v[118:121], v[42:45], v[138:141]
	v_mfma_f32_16x16x32_bf16 v[110:113], v[118:121], v[74:77], v[110:113]
	v_mfma_f32_16x16x32_bf16 v[138:141], v[126:129], v[38:41], v[114:117]
	v_mfma_f32_16x16x32_bf16 v[110:113], v[126:129], v[70:73], v[110:113]
	s_setprio 0
	s_nop 3
	v_add_u32_e32 v114, v176, v150
	v_add_u32_e32 v118, v176, v151
	v_add_u32_e32 v126, v176, v152
	v_add_u32_e32 v156, v176, v153
	ds_read_b128 v[114:117], v114
	ds_read_b128 v[118:121], v118
	ds_read_b128 v[126:129], v126
	ds_read_b128 v[156:159], v156
	s_setprio 1
	s_waitcnt lgkmcnt(0)
	v_mfma_f32_16x16x32_bf16 v[176:179], v[160:163], v[66:69], 0
	v_mfma_f32_16x16x32_bf16 v[160:163], v[160:163], v[98:101], 0
	v_mfma_f32_16x16x32_bf16 v[176:179], v[164:167], v[62:65], v[176:179]
	v_mfma_f32_16x16x32_bf16 v[160:163], v[164:167], v[94:97], v[160:163]
	v_mfma_f32_16x16x32_bf16 v[164:167], v[168:171], v[58:61], v[176:179]
	v_mfma_f32_16x16x32_bf16 v[160:163], v[168:171], v[90:93], v[160:163]
	v_mfma_f32_16x16x32_bf16 v[164:167], v[172:175], v[54:57], v[164:167]
	v_mfma_f32_16x16x32_bf16 v[160:163], v[172:175], v[86:89], v[160:163]
	s_setprio 0
	v_add_u32_e32 v184, 0x18000, v134
	v_add_u32_e32 v168, v184, v149
	v_add_u32_e32 v172, v184, v137
	v_add_u32_e32 v176, v184, v136
	v_add_u32_e32 v180, v184, v135
	ds_read_b128 v[168:171], v168
	ds_read_b128 v[172:175], v172
	ds_read_b128 v[176:179], v176
	ds_read_b128 v[180:183], v180
	s_setprio 1
	v_mfma_f32_16x16x32_bf16 v[164:167], v[114:117], v[50:53], v[164:167]
	v_mfma_f32_16x16x32_bf16 v[114:117], v[114:117], v[82:85], v[160:163]
	v_mfma_f32_16x16x32_bf16 v[160:163], v[118:121], v[46:49], v[164:167]
	v_mfma_f32_16x16x32_bf16 v[114:117], v[118:121], v[78:81], v[114:117]
	v_mfma_f32_16x16x32_bf16 v[118:121], v[126:129], v[42:45], v[160:163]
	v_mfma_f32_16x16x32_bf16 v[114:117], v[126:129], v[74:77], v[114:117]
	v_mfma_f32_16x16x32_bf16 v[160:163], v[156:159], v[38:41], v[118:121]
	v_mfma_f32_16x16x32_bf16 v[114:117], v[156:159], v[70:73], v[114:117]
	s_setprio 0
	s_nop 3
	v_add_u32_e32 v118, v184, v150
	v_add_u32_e32 v126, v184, v151
	v_add_u32_e32 v156, v184, v152
	v_add_u32_e32 v164, v184, v153
	ds_read_b128 v[118:121], v118
	ds_read_b128 v[126:129], v126
	ds_read_b128 v[156:159], v156
	ds_read_b128 v[164:167], v164
	s_setprio 1
	s_waitcnt lgkmcnt(0)
	v_mfma_f32_16x16x32_bf16 v[184:187], v[168:171], v[66:69], 0
	v_mfma_f32_16x16x32_bf16 v[168:171], v[168:171], v[98:101], 0
	v_mfma_f32_16x16x32_bf16 v[184:187], v[172:175], v[62:65], v[184:187]
	v_mfma_f32_16x16x32_bf16 v[168:171], v[172:175], v[94:97], v[168:171]
	v_mfma_f32_16x16x32_bf16 v[172:175], v[176:179], v[58:61], v[184:187]
	v_mfma_f32_16x16x32_bf16 v[168:171], v[176:179], v[90:93], v[168:171]
	v_mfma_f32_16x16x32_bf16 v[172:175], v[180:183], v[54:57], v[172:175]
	v_mfma_f32_16x16x32_bf16 v[168:171], v[180:183], v[86:89], v[168:171]
	s_setprio 0
	v_add_u32_e32 v192, 0x1a000, v134
	v_add_u32_e32 v176, v192, v149
	v_add_u32_e32 v180, v192, v137
	v_add_u32_e32 v184, v192, v136
	v_add_u32_e32 v188, v192, v135
	ds_read_b128 v[176:179], v176
	ds_read_b128 v[180:183], v180
	ds_read_b128 v[184:187], v184
	ds_read_b128 v[188:191], v188
	s_setprio 1
	v_mfma_f32_16x16x32_bf16 v[172:175], v[118:121], v[50:53], v[172:175]
	v_mfma_f32_16x16x32_bf16 v[118:121], v[118:121], v[82:85], v[168:171]
	v_mfma_f32_16x16x32_bf16 v[168:171], v[126:129], v[46:49], v[172:175]
	v_mfma_f32_16x16x32_bf16 v[118:121], v[126:129], v[78:81], v[118:121]
	v_mfma_f32_16x16x32_bf16 v[126:129], v[156:159], v[42:45], v[168:171]
	v_mfma_f32_16x16x32_bf16 v[118:121], v[156:159], v[74:77], v[118:121]
	v_mfma_f32_16x16x32_bf16 v[156:159], v[164:167], v[38:41], v[126:129]
	v_mfma_f32_16x16x32_bf16 v[118:121], v[164:167], v[70:73], v[118:121]
	s_setprio 0
	s_nop 3
	v_add_u32_e32 v126, v192, v150
	v_add_u32_e32 v164, v192, v151
	v_add_u32_e32 v168, v192, v152
	v_add_u32_e32 v172, v192, v153
	ds_read_b128 v[126:129], v126
	ds_read_b128 v[164:167], v164
	ds_read_b128 v[168:171], v168
	ds_read_b128 v[172:175], v172
	s_setprio 1
	s_waitcnt lgkmcnt(0)
	v_mfma_f32_16x16x32_bf16 v[192:195], v[176:179], v[66:69], 0
	v_mfma_f32_16x16x32_bf16 v[176:179], v[176:179], v[98:101], 0
	v_mfma_f32_16x16x32_bf16 v[192:195], v[180:183], v[62:65], v[192:195]
	v_mfma_f32_16x16x32_bf16 v[176:179], v[180:183], v[94:97], v[176:179]
	v_mfma_f32_16x16x32_bf16 v[180:183], v[184:187], v[58:61], v[192:195]
	v_mfma_f32_16x16x32_bf16 v[176:179], v[184:187], v[90:93], v[176:179]
	v_mfma_f32_16x16x32_bf16 v[180:183], v[188:191], v[54:57], v[180:183]
	v_mfma_f32_16x16x32_bf16 v[176:179], v[188:191], v[86:89], v[176:179]
	s_setprio 0
	v_add_u32_e32 v200, 0x1c000, v134
	v_add_u32_e32 v184, v200, v149
	v_add_u32_e32 v188, v200, v137
	v_add_u32_e32 v192, v200, v136
	v_add_u32_e32 v196, v200, v135
	ds_read_b128 v[184:187], v184
	ds_read_b128 v[188:191], v188
	ds_read_b128 v[192:195], v192
	ds_read_b128 v[196:199], v196
	s_setprio 1
	v_mfma_f32_16x16x32_bf16 v[180:183], v[126:129], v[50:53], v[180:183]
	v_mfma_f32_16x16x32_bf16 v[126:129], v[126:129], v[82:85], v[176:179]
	v_mfma_f32_16x16x32_bf16 v[176:179], v[164:167], v[46:49], v[180:183]
	v_mfma_f32_16x16x32_bf16 v[126:129], v[164:167], v[78:81], v[126:129]
	v_mfma_f32_16x16x32_bf16 v[164:167], v[168:171], v[42:45], v[176:179]
	v_mfma_f32_16x16x32_bf16 v[126:129], v[168:171], v[74:77], v[126:129]
	v_mfma_f32_16x16x32_bf16 v[164:167], v[172:175], v[38:41], v[164:167]
	v_mfma_f32_16x16x32_bf16 v[126:129], v[172:175], v[70:73], v[126:129]
	s_setprio 0
	v_add_u32_e32 v168, v200, v150
	v_add_u32_e32 v172, v200, v151
	v_add_u32_e32 v176, v200, v152
	v_add_u32_e32 v180, v200, v153
	ds_read_b128 v[168:171], v168
	ds_read_b128 v[172:175], v172
	ds_read_b128 v[176:179], v176
	ds_read_b128 v[180:183], v180
	s_setprio 1
	s_waitcnt lgkmcnt(0)
	v_mfma_f32_16x16x32_bf16 v[200:203], v[184:187], v[66:69], 0
	v_mfma_f32_16x16x32_bf16 v[184:187], v[184:187], v[98:101], 0
	v_mfma_f32_16x16x32_bf16 v[200:203], v[188:191], v[62:65], v[200:203]
	v_mfma_f32_16x16x32_bf16 v[184:187], v[188:191], v[94:97], v[184:187]
	v_mfma_f32_16x16x32_bf16 v[188:191], v[192:195], v[58:61], v[200:203]
	v_mfma_f32_16x16x32_bf16 v[184:187], v[192:195], v[90:93], v[184:187]
	v_mfma_f32_16x16x32_bf16 v[188:191], v[196:199], v[54:57], v[188:191]
	v_mfma_f32_16x16x32_bf16 v[184:187], v[196:199], v[86:89], v[184:187]
	s_setprio 0
	v_add_u32_e32 v208, 0x1e000, v134
	v_add_u32_e32 v134, v208, v149
	v_add_u32_e32 v137, v208, v137
	ds_read_b128 v[192:195], v134
	ds_read_b128 v[196:199], v137
	v_add_u32_e32 v134, v208, v136
	v_add_u32_e32 v135, v208, v135
	ds_read_b128 v[200:203], v134
	ds_read_b128 v[204:207], v135
	s_setprio 1
	v_mfma_f32_16x16x32_bf16 v[134:137], v[168:171], v[50:53], v[188:191]
	v_mfma_f32_16x16x32_bf16 v[168:171], v[168:171], v[82:85], v[184:187]
	v_mfma_f32_16x16x32_bf16 v[134:137], v[172:175], v[46:49], v[134:137]
	v_mfma_f32_16x16x32_bf16 v[168:171], v[172:175], v[78:81], v[168:171]
	v_mfma_f32_16x16x32_bf16 v[134:137], v[176:179], v[42:45], v[134:137]
	v_mfma_f32_16x16x32_bf16 v[168:171], v[176:179], v[74:77], v[168:171]
	v_mfma_f32_16x16x32_bf16 v[172:175], v[180:183], v[38:41], v[134:137]
	v_mfma_f32_16x16x32_bf16 v[134:137], v[180:183], v[70:73], v[168:171]
	s_setprio 0
	v_add_u32_e32 v149, v208, v150
	v_add_u32_e32 v150, v208, v151
	s_nop 2
	ds_read_b128 v[168:171], v149
	ds_read_b128 v[176:179], v150
	v_add_u32_e32 v149, v208, v152
	v_add_u32_e32 v180, v208, v153
	ds_read_b128 v[150:153], v149
	ds_read_b128 v[180:183], v180
	s_setprio 1
	s_waitcnt lgkmcnt(0)
	v_mfma_f32_16x16x32_bf16 v[66:69], v[192:195], v[66:69], 0
	v_mfma_f32_16x16x32_bf16 v[98:101], v[192:195], v[98:101], 0
	v_mfma_f32_16x16x32_bf16 v[62:65], v[196:199], v[62:65], v[66:69]
	v_mfma_f32_16x16x32_bf16 v[66:69], v[196:199], v[94:97], v[98:101]
	v_mfma_f32_16x16x32_bf16 v[58:61], v[200:203], v[58:61], v[62:65]
	v_mfma_f32_16x16x32_bf16 v[62:65], v[200:203], v[90:93], v[66:69]
	v_mfma_f32_16x16x32_bf16 v[54:57], v[204:207], v[54:57], v[58:61]
	v_mfma_f32_16x16x32_bf16 v[58:61], v[204:207], v[86:89], v[62:65]
	s_setprio 0
	s_setprio 1
	v_mfma_f32_16x16x32_bf16 v[50:53], v[168:171], v[50:53], v[54:57]
	v_mfma_f32_16x16x32_bf16 v[54:57], v[168:171], v[82:85], v[58:61]
	v_mfma_f32_16x16x32_bf16 v[46:49], v[176:179], v[46:49], v[50:53]
	v_mfma_f32_16x16x32_bf16 v[50:53], v[176:179], v[78:81], v[54:57]
	v_mfma_f32_16x16x32_bf16 v[42:45], v[150:153], v[42:45], v[46:49]
	v_mfma_f32_16x16x32_bf16 v[46:49], v[150:153], v[74:77], v[50:53]
	v_mfma_f32_16x16x32_bf16 v[50:53], v[180:183], v[38:41], v[42:45]
	v_mfma_f32_16x16x32_bf16 v[66:69], v[180:183], v[70:73], v[46:49]
	s_setprio 0
	v_mul_f32_e32 v39, v148, v130
	v_mul_f32_e32 v38, v148, v122
	v_exp_f32_e32 v40, v39
	v_mul_f32_e32 v39, v148, v123
	v_mul_f32_e32 v42, v148, v124
	v_mul_f32_e32 v44, v148, v125
	v_exp_f32_e32 v38, v38
	v_exp_f32_e32 v39, v39
	v_mul_f32_e32 v41, v148, v131
	v_exp_f32_e32 v42, v42
	v_mul_f32_e32 v43, v148, v132
	v_exp_f32_e32 v44, v44
	v_mul_f32_e32 v45, v148, v133
	v_exp_f32_e32 v41, v41
	v_exp_f32_e32 v43, v43
	v_exp_f32_e32 v45, v45
	v_add_f32_e32 v46, v38, v39
	v_add_f32_e32 v47, v42, v44
	v_add_f32_e32 v46, v46, v47
	v_add_f32_e32 v47, v40, v41
	v_add_f32_e32 v48, v43, v45
	v_add_f32_e32 v47, v47, v48
	v_cvt_pk_bf16_f32 v40, v40, v41
	v_cvt_pk_bf16_f32 v41, v43, v45
	v_mul_f32_e32 v43, v148, v160
	v_add_f32_e32 v46, v46, v47
	v_cvt_pk_bf16_f32 v38, v38, v39
	v_cvt_pk_bf16_f32 v39, v42, v44
	v_mul_f32_e32 v42, v148, v138
	v_exp_f32_e32 v44, v43
	v_mul_f32_e32 v43, v148, v139
	v_mul_f32_e32 v47, v148, v140
	v_mul_f32_e32 v49, v148, v141
	v_exp_f32_e32 v42, v42
	v_exp_f32_e32 v43, v43
	v_mul_f32_e32 v45, v148, v161
	v_exp_f32_e32 v47, v47
	v_mul_f32_e32 v48, v148, v162
	v_exp_f32_e32 v49, v49
	v_mul_f32_e32 v54, v148, v163
	v_exp_f32_e32 v45, v45
	v_exp_f32_e32 v48, v48
	v_exp_f32_e32 v54, v54
	v_add_f32_e32 v55, v42, v43
	v_add_f32_e32 v56, v47, v49
	v_add_f32_e32 v55, v55, v56
	v_add_f32_e32 v56, v44, v45
	v_add_f32_e32 v57, v48, v54
	v_add_f32_e32 v56, v56, v57
	v_add_f32_e32 v46, v155, v46
	v_add_f32_e32 v55, v55, v56
	v_add_f32_e32 v46, v46, v55
	v_cvt_pk_bf16_f32 v42, v42, v43
	v_cvt_pk_bf16_f32 v43, v47, v49
	v_mul_f32_e32 v47, v148, v156
	v_mul_f32_e32 v49, v148, v157
	v_mul_f32_e32 v55, v148, v158
	v_mul_f32_e32 v57, v148, v159
	v_cvt_pk_bf16_f32 v44, v44, v45
	v_cvt_pk_bf16_f32 v45, v48, v54
	v_exp_f32_e32 v47, v47
	v_mul_f32_e32 v48, v148, v164
	v_exp_f32_e32 v49, v49
	v_mul_f32_e32 v54, v148, v165
	v_exp_f32_e32 v55, v55
	v_mul_f32_e32 v56, v148, v166
	v_exp_f32_e32 v57, v57
	v_mul_f32_e32 v58, v148, v167
	v_exp_f32_e32 v48, v48
	v_exp_f32_e32 v54, v54
	v_exp_f32_e32 v56, v56
	v_exp_f32_e32 v58, v58
	v_add_f32_e32 v59, v47, v49
	v_add_f32_e32 v60, v55, v57
	v_add_f32_e32 v59, v59, v60
	v_add_f32_e32 v60, v48, v54
	v_add_f32_e32 v61, v56, v58
	v_add_f32_e32 v60, v60, v61
	v_add_f32_e32 v59, v59, v60
	v_mul_f32_e32 v50, v148, v50
	v_mul_f32_e32 v51, v148, v51
	v_mul_f32_e32 v52, v148, v52
	v_add_f32_e32 v59, v46, v59
	v_cvt_pk_bf16_f32 v46, v47, v49
	v_cvt_pk_bf16_f32 v47, v55, v57
	v_cvt_pk_bf16_f32 v48, v48, v54
	v_cvt_pk_bf16_f32 v49, v56, v58
	v_mul_f32_e32 v54, v148, v172
	v_exp_f32_e32 v55, v50
	v_mul_f32_e32 v50, v148, v173
	v_exp_f32_e32 v56, v51
	v_mul_f32_e32 v51, v148, v174
	v_exp_f32_e32 v57, v52
	v_mul_f32_e32 v52, v148, v175
	v_exp_f32_e32 v54, v54
	v_exp_f32_e32 v50, v50
	v_exp_f32_e32 v51, v51
	v_exp_f32_e32 v52, v52
	v_mul_f32_e32 v53, v148, v53
	v_exp_f32_e32 v53, v53
	v_add_f32_e32 v58, v54, v50
	v_add_f32_e32 v60, v51, v52
	v_add_f32_e32 v58, v58, v60
	v_add_f32_e32 v60, v55, v56
	v_add_f32_e32 v61, v57, v53
	v_add_f32_e32 v60, v60, v61
	v_add_f32_e32 v58, v58, v60
	v_cvt_pk_bf16_f32 v51, v51, v52
	v_cvt_pk_bf16_f32 v52, v55, v56
	v_mul_f32_e32 v55, v147, v106
	v_add_f32_e32 v74, v59, v58
	v_cvt_pk_bf16_f32 v50, v54, v50
	v_mul_f32_e32 v54, v147, v102
	v_exp_f32_e32 v56, v55
	v_mul_f32_e32 v55, v147, v103
	v_mul_f32_e32 v58, v147, v104
	v_mul_f32_e32 v60, v147, v105
	v_cvt_pk_bf16_f32 v53, v57, v53
	v_exp_f32_e32 v54, v54
	v_exp_f32_e32 v55, v55
	v_mul_f32_e32 v57, v147, v107
	v_exp_f32_e32 v58, v58
	v_mul_f32_e32 v59, v147, v108
	v_exp_f32_e32 v60, v60
	v_mul_f32_e32 v61, v147, v109
	v_exp_f32_e32 v57, v57
	v_exp_f32_e32 v59, v59
	v_exp_f32_e32 v61, v61
	v_add_f32_e32 v62, v54, v55
	v_add_f32_e32 v63, v58, v60
	v_add_f32_e32 v62, v62, v63
	v_add_f32_e32 v63, v56, v57
	v_add_f32_e32 v64, v59, v61
	v_add_f32_e32 v63, v63, v64
	v_cvt_pk_bf16_f32 v56, v56, v57
	v_cvt_pk_bf16_f32 v57, v59, v61
	v_mul_f32_e32 v59, v147, v114
	v_add_f32_e32 v62, v62, v63
	v_cvt_pk_bf16_f32 v54, v54, v55
	v_cvt_pk_bf16_f32 v55, v58, v60
	v_mul_f32_e32 v58, v147, v110
	v_exp_f32_e32 v60, v59
	v_mul_f32_e32 v59, v147, v111
	v_mul_f32_e32 v63, v147, v112
	v_mul_f32_e32 v65, v147, v113
	v_exp_f32_e32 v58, v58
	v_exp_f32_e32 v59, v59
	v_mul_f32_e32 v61, v147, v115
	v_exp_f32_e32 v63, v63
	v_mul_f32_e32 v64, v147, v116
	v_exp_f32_e32 v65, v65
	v_mul_f32_e32 v70, v147, v117
	v_exp_f32_e32 v61, v61
	v_exp_f32_e32 v64, v64
	v_exp_f32_e32 v70, v70
	v_add_f32_e32 v71, v58, v59
	v_add_f32_e32 v72, v63, v65
	v_add_f32_e32 v71, v71, v72
	v_add_f32_e32 v72, v60, v61
	v_add_f32_e32 v73, v64, v70
	v_add_f32_e32 v72, v72, v73
	v_add_f32_e32 v62, v154, v62
	v_add_f32_e32 v71, v71, v72
	v_add_f32_e32 v62, v62, v71
	v_cvt_pk_bf16_f32 v58, v58, v59
	v_cvt_pk_bf16_f32 v59, v63, v65
	v_mul_f32_e32 v63, v147, v118
	v_mul_f32_e32 v65, v147, v119
	v_mul_f32_e32 v71, v147, v120
	v_mul_f32_e32 v73, v147, v121
	v_cvt_pk_bf16_f32 v60, v60, v61
	v_cvt_pk_bf16_f32 v61, v64, v70
	v_exp_f32_e32 v63, v63
	v_mul_f32_e32 v64, v147, v126
	v_exp_f32_e32 v65, v65
	v_mul_f32_e32 v70, v147, v127
	v_exp_f32_e32 v71, v71
	v_mul_f32_e32 v72, v147, v128
	v_exp_f32_e32 v73, v73
	v_mul_f32_e32 v75, v147, v129
	v_exp_f32_e32 v64, v64
	v_exp_f32_e32 v70, v70
	v_exp_f32_e32 v72, v72
	v_exp_f32_e32 v75, v75
	v_add_f32_e32 v76, v63, v65
	v_add_f32_e32 v77, v71, v73
	v_add_f32_e32 v76, v76, v77
	v_add_f32_e32 v77, v64, v70
	v_add_f32_e32 v78, v72, v75
	v_add_f32_e32 v77, v77, v78
	v_add_f32_e32 v76, v76, v77
	v_mul_f32_e32 v66, v147, v66
	v_mul_f32_e32 v67, v147, v67
	v_mul_f32_e32 v68, v147, v68
	v_add_f32_e32 v76, v62, v76
	v_cvt_pk_bf16_f32 v62, v63, v65
	v_cvt_pk_bf16_f32 v63, v71, v73
	v_cvt_pk_bf16_f32 v64, v64, v70
	v_cvt_pk_bf16_f32 v65, v72, v75
	v_mul_f32_e32 v70, v147, v134
	v_exp_f32_e32 v71, v66
	v_mul_f32_e32 v66, v147, v135
	v_exp_f32_e32 v72, v67
	v_mul_f32_e32 v67, v147, v136
	v_exp_f32_e32 v73, v68
	v_mul_f32_e32 v68, v147, v137
	v_exp_f32_e32 v70, v70
	v_exp_f32_e32 v66, v66
	v_exp_f32_e32 v67, v67
	v_exp_f32_e32 v68, v68
	v_mul_f32_e32 v69, v147, v69
	v_exp_f32_e32 v69, v69
	v_add_f32_e32 v75, v70, v66
	v_add_f32_e32 v77, v67, v68
	v_add_f32_e32 v75, v75, v77
	v_add_f32_e32 v77, v71, v72
	v_add_f32_e32 v78, v73, v69
	v_add_f32_e32 v77, v77, v78
	v_add_f32_e32 v75, v75, v77
	v_add_f32_e32 v75, v76, v75
	s_waitcnt vmcnt(0)
	s_barrier
	s_add_i32 s9, s8, 64
	v_ashrrev_i32_e32 v76, 5, v5
	v_cvt_pk_bf16_f32 v66, v70, v66
	v_lshl_add_u32 v70, s9, 1, v76
	v_cvt_pk_bf16_f32 v67, v67, v68
	v_cvt_pk_bf16_f32 v68, v71, v72
	v_lshrrev_b32_e32 v71, 1, v70
	v_and_b32_e32 v5, 31, v5
	v_and_b32_e32 v71, 12, v71
	v_and_b32_e32 v77, 3, v76
	v_bitop3_b32 v72, v71, v5, v77 bitop3:0x36
	v_ashrrev_i32_e32 v71, 31, v70
	v_lshlrev_b64 v[70:71], 9, v[70:71]
	v_cvt_pk_bf16_f32 v69, v73, v69
	v_lshl_add_u64 v[70:71], s[4:5], 0, v[70:71]
	v_lshlrev_b32_e32 v72, 4, v72
	v_mov_b32_e32 v73, v4
	s_lshl_b32 s9, s9, 10
	v_lshl_add_u64 v[70:71], v[70:71], 0, v[72:73]
	s_add_i32 m0, s9, 0
	s_add_i32 s9, s8, 0x41
	global_load_lds_dwordx4 v[70:71], off
	v_lshl_add_u32 v70, s9, 1, v76
	v_lshrrev_b32_e32 v71, 1, v70
	v_and_b32_e32 v71, 12, v71
	v_and_b32_e32 v72, 3, v70
	v_bitop3_b32 v72, v71, v5, v72 bitop3:0x36
	v_ashrrev_i32_e32 v71, 31, v70
	v_lshlrev_b64 v[70:71], 9, v[70:71]
	v_lshl_add_u64 v[70:71], s[4:5], 0, v[70:71]
	v_lshlrev_b32_e32 v72, 4, v72
	s_lshl_b32 s9, s9, 10
	v_lshl_add_u64 v[70:71], v[70:71], 0, v[72:73]
	s_add_i32 m0, s9, 0
	s_add_i32 s9, s8, 0x42
	global_load_lds_dwordx4 v[70:71], off
	v_lshl_add_u32 v70, s9, 1, v76
	v_lshrrev_b32_e32 v71, 1, v70
	v_and_b32_e32 v71, 12, v71
	v_bitop3_b32 v72, v71, v5, v77 bitop3:0x36
	v_ashrrev_i32_e32 v71, 31, v70
	v_lshlrev_b64 v[70:71], 9, v[70:71]
	v_lshl_add_u64 v[70:71], s[4:5], 0, v[70:71]
	v_lshlrev_b32_e32 v72, 4, v72
	s_lshl_b32 s9, s9, 10
	v_lshl_add_u64 v[70:71], v[70:71], 0, v[72:73]
	s_add_i32 m0, s9, 0
	s_add_i32 s9, s8, 0x43
	global_load_lds_dwordx4 v[70:71], off
	v_lshl_add_u32 v70, s9, 1, v76
	v_lshrrev_b32_e32 v71, 1, v70
	v_and_b32_e32 v71, 12, v71
	v_and_b32_e32 v72, 3, v70
	v_bitop3_b32 v72, v71, v5, v72 bitop3:0x36
	v_ashrrev_i32_e32 v71, 31, v70
	v_lshlrev_b64 v[70:71], 9, v[70:71]
	v_lshl_add_u64 v[70:71], s[4:5], 0, v[70:71]
	v_lshlrev_b32_e32 v72, 4, v72
	s_lshl_b32 s9, s9, 10
	v_lshl_add_u64 v[70:71], v[70:71], 0, v[72:73]
	s_add_i32 m0, s9, 0
	s_add_i32 s9, s8, 0x44
	global_load_lds_dwordx4 v[70:71], off
	v_lshl_add_u32 v70, s9, 1, v76
	v_lshrrev_b32_e32 v71, 1, v70
	v_and_b32_e32 v71, 12, v71
	v_bitop3_b32 v72, v71, v5, v77 bitop3:0x36
	v_ashrrev_i32_e32 v71, 31, v70
	v_lshlrev_b64 v[70:71], 9, v[70:71]
	v_lshl_add_u64 v[70:71], s[4:5], 0, v[70:71]
	v_lshlrev_b32_e32 v72, 4, v72
	s_lshl_b32 s9, s9, 10
	v_lshl_add_u64 v[70:71], v[70:71], 0, v[72:73]
	s_add_i32 m0, s9, 0
	s_add_i32 s9, s8, 0x45
	global_load_lds_dwordx4 v[70:71], off
	v_lshl_add_u32 v70, s9, 1, v76
	v_lshrrev_b32_e32 v71, 1, v70
	v_and_b32_e32 v71, 12, v71
	v_and_b32_e32 v72, 3, v70
	v_bitop3_b32 v72, v71, v5, v72 bitop3:0x36
	v_ashrrev_i32_e32 v71, 31, v70
	v_lshlrev_b64 v[70:71], 9, v[70:71]
	v_lshl_add_u64 v[70:71], s[4:5], 0, v[70:71]
	v_lshlrev_b32_e32 v72, 4, v72
	s_lshl_b32 s9, s9, 10
	v_lshl_add_u64 v[70:71], v[70:71], 0, v[72:73]
	s_add_i32 m0, s9, 0
	s_add_i32 s9, s8, 0x46
	global_load_lds_dwordx4 v[70:71], off
	v_lshl_add_u32 v70, s9, 1, v76
	v_lshrrev_b32_e32 v71, 1, v70
	v_and_b32_e32 v71, 12, v71
	v_bitop3_b32 v72, v71, v5, v77 bitop3:0x36
	v_ashrrev_i32_e32 v71, 31, v70
	v_lshlrev_b64 v[70:71], 9, v[70:71]
	v_lshl_add_u64 v[70:71], s[4:5], 0, v[70:71]
	v_lshlrev_b32_e32 v72, 4, v72
	s_lshl_b32 s9, s9, 10
	v_lshl_add_u64 v[70:71], v[70:71], 0, v[72:73]
	s_add_i32 m0, s9, 0
	s_addk_i32 s8, 0x47
	global_load_lds_dwordx4 v[70:71], off
	v_lshl_add_u32 v70, s8, 1, v76
	v_lshrrev_b32_e32 v71, 1, v70
	v_and_b32_e32 v71, 12, v71
	v_and_b32_e32 v72, 3, v70
	v_bitop3_b32 v5, v71, v5, v72 bitop3:0x36
	v_ashrrev_i32_e32 v71, 31, v70
	v_lshlrev_b64 v[70:71], 9, v[70:71]
	v_lshl_add_u64 v[70:71], s[4:5], 0, v[70:71]
	v_lshlrev_b32_e32 v72, 4, v5
	s_lshl_b32 s4, s8, 10
	v_lshl_add_u64 v[70:71], v[70:71], 0, v[72:73]
	s_add_i32 m0, s4, 0
	v_mov_b32_e32 v5, v74
	global_load_lds_dwordx4 v[70:71], off
	s_nop 0
	v_permlane16_swap_b32_e32 v74, v5
	v_add_f32_e32 v5, v74, v5
	v_mov_b32_e32 v70, v5
	s_nop 1
	v_permlane32_swap_b32_e32 v5, v70
	v_add_f32_e32 v5, v5, v70
	v_div_scale_f32 v70, s[4:5], v5, v5, 1.0
	v_rcp_f32_e32 v71, v70
	v_lshl_add_u64 v[2:3], s[2:3], 0, v[2:3]
	v_bfe_u32 v87, v145, 5, 1
	v_lshl_add_u64 v[2:3], v[2:3], 0, s[6:7]
	v_fma_f32 v72, -v70, v71, 1.0
	v_fmac_f32_e32 v71, v72, v71
	v_div_scale_f32 v72, vcc, 1.0, v5, 1.0
	v_mul_f32_e32 v73, v72, v71
	v_fma_f32 v74, -v70, v73, v72
	v_fmac_f32_e32 v73, v74, v71
	v_fma_f32 v70, -v70, v73, v72
	v_div_fmas_f32 v70, v70, v71, v73
	v_div_fixup_f32 v5, v70, v5, 1.0
	v_mov_b32_e32 v70, v75
	s_nop 1
	v_permlane16_swap_b32_e32 v75, v70
	v_add_f32_e32 v70, v75, v70
	v_mov_b32_e32 v71, v70
	s_nop 1
	v_permlane32_swap_b32_e32 v70, v71
	v_add_f32_e32 v70, v70, v71
	v_div_scale_f32 v71, s[4:5], v70, v70, 1.0
	v_rcp_f32_e32 v72, v71
	v_bitop3_b32 v76, v87, v144, 8 bitop3:0x36
	v_bitop3_b32 v77, v87, v144, 10 bitop3:0x36
	v_bitop3_b32 v78, v87, v144, 12 bitop3:0x36
	v_fma_f32 v73, -v71, v72, 1.0
	v_fmac_f32_e32 v72, v73, v72
	v_div_scale_f32 v73, vcc, 1.0, v70, 1.0
	v_mul_f32_e32 v74, v73, v72
	v_fma_f32 v75, -v71, v74, v73
	v_fmac_f32_e32 v74, v75, v72
	v_fma_f32 v71, -v71, v74, v73
	v_div_fmas_f32 v71, v71, v72, v74
	v_lshlrev_b32_e32 v72, 1, v145
	v_and_b32_e32 v73, 3, v145
	v_and_or_b32 v72, v72, 24, v73
	v_and_b32_e32 v73, 8, v146
	v_lshlrev_b32_e32 v72, 9, v72
	v_add3_u32 v146, 0, v73, v72
	v_bitop3_b32 v72, v87, v145, 15 bitop3:0x78
	v_bitop3_b32 v73, v87, v144, 2 bitop3:0x36
	v_bitop3_b32 v74, v87, v144, 4 bitop3:0x36
	v_bitop3_b32 v75, v87, v144, 6 bitop3:0x36
	v_bitop3_b32 v79, v87, v144, 14 bitop3:0x36
	v_bitop3_b32 v80, v87, v144, 16 bitop3:0x36
	v_bitop3_b32 v81, v87, v144, 18 bitop3:0x36
	v_bitop3_b32 v82, v87, v144, 20 bitop3:0x36
	v_bitop3_b32 v83, v87, v144, 22 bitop3:0x36
	v_bitop3_b32 v84, v87, v144, 24 bitop3:0x36
	v_bitop3_b32 v85, v87, v144, 26 bitop3:0x36
	v_bitop3_b32 v86, v87, v144, 28 bitop3:0x36
	v_bitop3_b32 v87, v87, v144, 30 bitop3:0x36
	v_div_fixup_f32 v136, v71, v70, 1.0
	v_lshl_add_u64 v[70:71], v[2:3], 0, v[142:143]
	v_lshlrev_b32_e32 v149, 4, v72
	v_lshlrev_b32_e32 v151, 4, v73
	v_lshlrev_b32_e32 v153, 4, v74
	v_lshlrev_b32_e32 v154, 4, v75
	v_lshlrev_b32_e32 v143, 4, v76
	v_lshlrev_b32_e32 v147, 4, v77
	v_lshlrev_b32_e32 v150, 4, v78
	v_lshlrev_b32_e32 v152, 4, v79
	v_lshlrev_b32_e32 v139, 4, v80
	v_lshlrev_b32_e32 v141, 4, v81
	v_lshlrev_b32_e32 v145, 4, v82
	v_lshlrev_b32_e32 v148, 4, v83
	v_lshlrev_b32_e32 v137, 4, v84
	v_lshlrev_b32_e32 v138, 4, v85
	v_lshlrev_b32_e32 v140, 4, v86
	v_lshlrev_b32_e32 v142, 4, v87
	v_add_u32_e32 v72, v146, v149
	v_add_u32_e32 v73, v146, v151
	v_add_u32_e32 v74, v146, v153
	v_add_u32_e32 v75, v146, v154
	v_add_u32_e32 v76, v146, v143
	v_add_u32_e32 v77, v146, v147
	v_add_u32_e32 v78, v146, v150
	v_add_u32_e32 v79, v146, v152
	v_add_u32_e32 v80, v146, v139
	v_add_u32_e32 v81, v146, v141
	v_add_u32_e32 v82, v146, v145
	v_add_u32_e32 v83, v146, v148
	v_add_u32_e32 v84, v146, v137
	v_add_u32_e32 v85, v146, v138
	v_add_u32_e32 v86, v146, v140
	v_add_u32_e32 v87, v146, v142
	s_waitcnt vmcnt(8)
	s_waitcnt lgkmcnt(0)
	s_barrier
	ds_read2st64_b64 v[88:91], v72 offset1:4
	ds_read2st64_b64 v[92:95], v73 offset1:4
	ds_read2st64_b64 v[96:99], v74 offset1:4
	ds_read2st64_b64 v[100:103], v75 offset1:4
	ds_read2st64_b64 v[104:107], v76 offset1:4
	ds_read2st64_b64 v[108:111], v77 offset1:4
	ds_read2st64_b64 v[112:115], v78 offset1:4
	ds_read2st64_b64 v[116:119], v79 offset1:4
	ds_read2st64_b64 v[120:123], v80 offset1:4
	ds_read2st64_b64 v[124:127], v81 offset1:4
	ds_read2st64_b64 v[128:131], v82 offset1:4
	ds_read2st64_b64 v[132:135], v83 offset1:4
	ds_read2st64_b64 v[156:159], v84 offset1:4
	ds_read2st64_b64 v[160:163], v85 offset1:4
	ds_read2st64_b64 v[164:167], v86 offset1:4
	ds_read2st64_b64 v[168:171], v87 offset1:4
	s_mov_b64 s[2:3], 0xae00000
	v_lshl_add_u64 v[2:3], v[70:71], 0, s[2:3]
	s_setprio 1
	s_waitcnt lgkmcnt(14)
	v_mov_b32_e32 v172, v88
	v_mov_b32_e32 v173, v89
	v_mov_b32_e32 v174, v92
	v_mov_b32_e32 v175, v93
	s_waitcnt lgkmcnt(13)
	v_mov_b32_e32 v180, v96
	v_mov_b32_e32 v181, v97
	s_waitcnt lgkmcnt(12)
	v_mov_b32_e32 v182, v100
	v_mov_b32_e32 v183, v101
	v_mfma_f32_16x16x32_bf16 v[176:179], v[172:175], v[6:9], 0
	v_mfma_f32_16x16x32_bf16 v[172:175], v[172:175], v[22:25], 0
	v_mfma_f32_16x16x32_bf16 v[176:179], v[180:183], v[10:13], v[176:179]
	v_mfma_f32_16x16x32_bf16 v[172:175], v[180:183], v[26:29], v[172:175]
	s_waitcnt lgkmcnt(11)
	v_mov_b32_e32 v180, v104
	v_mov_b32_e32 v181, v105
	s_waitcnt lgkmcnt(10)
	v_mov_b32_e32 v182, v108
	v_mov_b32_e32 v183, v109
	s_nop 1
	v_mfma_f32_16x16x32_bf16 v[176:179], v[180:183], v[14:17], v[176:179]
	v_mfma_f32_16x16x32_bf16 v[172:175], v[180:183], v[30:33], v[172:175]
	s_waitcnt lgkmcnt(9)
	v_mov_b32_e32 v180, v112
	v_mov_b32_e32 v181, v113
	s_waitcnt lgkmcnt(8)
	v_mov_b32_e32 v182, v116
	v_mov_b32_e32 v183, v117
	s_nop 1
	v_mfma_f32_16x16x32_bf16 v[176:179], v[180:183], v[18:21], v[176:179]
	v_mfma_f32_16x16x32_bf16 v[172:175], v[180:183], v[34:37], v[172:175]
	s_waitcnt lgkmcnt(7)
	v_mov_b32_e32 v180, v120
	v_mov_b32_e32 v181, v121
	s_waitcnt lgkmcnt(6)
	v_mov_b32_e32 v182, v124
	v_mov_b32_e32 v183, v125
	s_nop 1
	v_mfma_f32_16x16x32_bf16 v[176:179], v[180:183], v[38:41], v[176:179]
	v_mfma_f32_16x16x32_bf16 v[172:175], v[180:183], v[54:57], v[172:175]
	s_waitcnt lgkmcnt(5)
	v_mov_b32_e32 v180, v128
	v_mov_b32_e32 v181, v129
	s_waitcnt lgkmcnt(4)
	v_mov_b32_e32 v182, v132
	v_mov_b32_e32 v183, v133
	s_nop 1
	v_mfma_f32_16x16x32_bf16 v[176:179], v[180:183], v[42:45], v[176:179]
	v_mfma_f32_16x16x32_bf16 v[172:175], v[180:183], v[58:61], v[172:175]
	s_waitcnt lgkmcnt(3)
	v_mov_b32_e32 v180, v156
	v_mov_b32_e32 v181, v157
	s_waitcnt lgkmcnt(2)
	v_mov_b32_e32 v182, v160
	v_mov_b32_e32 v183, v161
	s_nop 1
	v_mfma_f32_16x16x32_bf16 v[176:179], v[180:183], v[46:49], v[176:179]
	v_mfma_f32_16x16x32_bf16 v[172:175], v[180:183], v[62:65], v[172:175]
	s_waitcnt lgkmcnt(1)
	v_mov_b32_e32 v180, v164
	v_mov_b32_e32 v181, v165
	s_waitcnt lgkmcnt(0)
	v_mov_b32_e32 v182, v168
	v_mov_b32_e32 v183, v169
	s_nop 1
	v_mfma_f32_16x16x32_bf16 v[176:179], v[180:183], v[50:53], v[176:179]
	v_mfma_f32_16x16x32_bf16 v[172:175], v[180:183], v[66:69], v[172:175]
	s_setprio 0
	s_nop 5
	v_mul_f32_e32 v88, v5, v176
	v_mul_f32_e32 v89, v5, v177
	v_cvt_pk_bf16_f32 v88, v88, v89
	v_mul_f32_e32 v89, v5, v178
	v_mul_f32_e32 v92, v5, v179
	v_cvt_pk_bf16_f32 v89, v89, v92
	v_mul_f32_e32 v92, v136, v172
	v_mul_f32_e32 v93, v136, v173
	v_cvt_pk_bf16_f32 v96, v92, v93
	v_mul_f32_e32 v92, v136, v174
	v_mul_f32_e32 v93, v136, v175
	ds_read_b64 v[172:173], v72 offset:16384
	ds_read_b64 v[174:175], v73 offset:16384
	ds_read_b64 v[176:177], v74 offset:16384
	ds_read_b64 v[178:179], v75 offset:16384
	ds_read_b64 v[180:181], v76 offset:16384
	ds_read_b64 v[182:183], v77 offset:16384
	ds_read_b64 v[184:185], v78 offset:16384
	ds_read_b64 v[186:187], v79 offset:16384
	ds_read_b64 v[188:189], v80 offset:16384
	ds_read_b64 v[190:191], v81 offset:16384
	ds_read_b64 v[192:193], v82 offset:16384
	ds_read_b64 v[194:195], v83 offset:16384
	ds_read_b64 v[196:197], v84 offset:16384
	ds_read_b64 v[198:199], v85 offset:16384
	ds_read_b64 v[200:201], v86 offset:16384
	ds_read_b64 v[202:203], v87 offset:16384
	v_cvt_pk_bf16_f32 v97, v92, v93
	s_setprio 1
	v_mov_b32_e32 v92, v90
	v_mov_b32_e32 v93, v91
	v_mov_b32_e32 v100, v98
	v_mov_b32_e32 v101, v99
	v_mov_b32_e32 v108, v106
	v_mfma_f32_16x16x32_bf16 v[204:207], v[92:95], v[6:9], 0
	v_mov_b32_e32 v109, v107
	v_mov_b32_e32 v116, v114
	v_mov_b32_e32 v117, v115
	v_mfma_f32_16x16x32_bf16 v[90:93], v[92:95], v[22:25], 0
	v_mov_b32_e32 v124, v122
	v_mov_b32_e32 v125, v123
	v_mov_b32_e32 v132, v130
	v_mfma_f32_16x16x32_bf16 v[204:207], v[100:103], v[10:13], v[204:207]
	v_mov_b32_e32 v133, v131
	v_mov_b32_e32 v160, v158
	v_mov_b32_e32 v161, v159
	v_mfma_f32_16x16x32_bf16 v[90:93], v[100:103], v[26:29], v[90:93]
	v_mov_b32_e32 v168, v166
	v_mov_b32_e32 v169, v167
	v_mfma_f32_16x16x32_bf16 v[98:101], v[108:111], v[14:17], v[204:207]
	v_mfma_f32_16x16x32_bf16 v[90:93], v[108:111], v[30:33], v[90:93]
	v_mfma_f32_16x16x32_bf16 v[98:101], v[116:119], v[18:21], v[98:101]
	v_mfma_f32_16x16x32_bf16 v[90:93], v[116:119], v[34:37], v[90:93]
	v_mfma_f32_16x16x32_bf16 v[98:101], v[124:127], v[38:41], v[98:101]
	v_mfma_f32_16x16x32_bf16 v[90:93], v[124:127], v[54:57], v[90:93]
	v_mfma_f32_16x16x32_bf16 v[98:101], v[132:135], v[42:45], v[98:101]
	v_mfma_f32_16x16x32_bf16 v[90:93], v[132:135], v[58:61], v[90:93]
	v_mfma_f32_16x16x32_bf16 v[98:101], v[160:163], v[46:49], v[98:101]
	v_mfma_f32_16x16x32_bf16 v[90:93], v[160:163], v[62:65], v[90:93]
	v_mfma_f32_16x16x32_bf16 v[98:101], v[168:171], v[50:53], v[98:101]
	v_mfma_f32_16x16x32_bf16 v[92:95], v[168:171], v[66:69], v[90:93]
	s_setprio 0
	s_nop 5
	v_mul_f32_e32 v90, v5, v98
	v_mul_f32_e32 v91, v5, v99
	v_cvt_pk_bf16_f32 v90, v90, v91
	v_mul_f32_e32 v91, v5, v100
	v_mul_f32_e32 v98, v5, v101
	v_mul_f32_e32 v92, v136, v92
	v_cvt_pk_bf16_f32 v91, v91, v98
	v_mul_f32_e32 v93, v136, v93
	v_cvt_pk_bf16_f32 v98, v92, v93
	v_mul_f32_e32 v92, v136, v94
	s_mov_b32 s2, 0xae00000
	v_mul_f32_e32 v93, v136, v95
	v_cvt_pk_bf16_f32 v99, v92, v93
	v_add_co_u32_e32 v92, vcc, s2, v70
	s_mov_b32 s2, 0xae08000
	s_nop 0
	v_addc_co_u32_e32 v93, vcc, 0, v71, vcc
	v_add_co_u32_e32 v134, vcc, s2, v70
	global_store_dwordx4 v[92:93], v[88:91], off sc1
	s_nop 0
	v_addc_co_u32_e32 v135, vcc, 0, v71, vcc
	global_store_dwordx4 v[134:135], v[96:99], off sc1
	ds_read_b64 v[88:89], v72 offset:18432
	ds_read_b64 v[90:91], v73 offset:18432
	ds_read_b64 v[92:93], v74 offset:18432
	ds_read_b64 v[94:95], v75 offset:18432
	ds_read_b64 v[96:97], v76 offset:18432
	ds_read_b64 v[98:99], v77 offset:18432
	ds_read_b64 v[100:101], v78 offset:18432
	ds_read_b64 v[102:103], v79 offset:18432
	ds_read_b64 v[104:105], v80 offset:18432
	ds_read_b64 v[106:107], v81 offset:18432
	ds_read_b64 v[108:109], v82 offset:18432
	ds_read_b64 v[110:111], v83 offset:18432
	ds_read_b64 v[112:113], v84 offset:18432
	ds_read_b64 v[114:115], v85 offset:18432
	ds_read_b64 v[116:117], v86 offset:18432
	ds_read_b64 v[118:119], v87 offset:18432
	s_setprio 1
	s_waitcnt lgkmcnt(14)
	v_mfma_f32_16x16x32_bf16 v[120:123], v[172:175], v[6:9], 0
	v_mfma_f32_16x16x32_bf16 v[124:127], v[172:175], v[22:25], 0
	v_mfma_f32_16x16x32_bf16 v[120:123], v[176:179], v[10:13], v[120:123]
	v_mfma_f32_16x16x32_bf16 v[124:127], v[176:179], v[26:29], v[124:127]
	v_mfma_f32_16x16x32_bf16 v[120:123], v[180:183], v[14:17], v[120:123]
	v_mfma_f32_16x16x32_bf16 v[124:127], v[180:183], v[30:33], v[124:127]
	v_mfma_f32_16x16x32_bf16 v[120:123], v[184:187], v[18:21], v[120:123]
	v_mfma_f32_16x16x32_bf16 v[124:127], v[184:187], v[34:37], v[124:127]
	v_mfma_f32_16x16x32_bf16 v[120:123], v[188:191], v[38:41], v[120:123]
	v_mfma_f32_16x16x32_bf16 v[124:127], v[188:191], v[54:57], v[124:127]
	v_mfma_f32_16x16x32_bf16 v[120:123], v[192:195], v[42:45], v[120:123]
	v_mfma_f32_16x16x32_bf16 v[124:127], v[192:195], v[58:61], v[124:127]
	v_mfma_f32_16x16x32_bf16 v[120:123], v[196:199], v[46:49], v[120:123]
	v_mfma_f32_16x16x32_bf16 v[124:127], v[196:199], v[62:65], v[124:127]
	v_mfma_f32_16x16x32_bf16 v[120:123], v[200:203], v[50:53], v[120:123]
	v_mfma_f32_16x16x32_bf16 v[124:127], v[200:203], v[66:69], v[124:127]
	s_setprio 0
	ds_read_b64 v[128:129], v72 offset:32768
	ds_read_b64 v[130:131], v73 offset:32768
	ds_read_b64 v[156:157], v74 offset:32768
	ds_read_b64 v[158:159], v75 offset:32768
	ds_read_b64 v[160:161], v76 offset:32768
	ds_read_b64 v[162:163], v77 offset:32768
	ds_read_b64 v[164:165], v78 offset:32768
	ds_read_b64 v[166:167], v79 offset:32768
	ds_read_b64 v[168:169], v80 offset:32768
	ds_read_b64 v[170:171], v81 offset:32768
	ds_read_b64 v[172:173], v82 offset:32768
	ds_read_b64 v[174:175], v83 offset:32768
	ds_read_b64 v[176:177], v84 offset:32768
	ds_read_b64 v[178:179], v85 offset:32768
	ds_read_b64 v[180:181], v86 offset:32768
	ds_read_b64 v[182:183], v87 offset:32768
	v_mul_f32_e32 v70, v5, v120
	v_mul_f32_e32 v71, v5, v121
	v_cvt_pk_bf16_f32 v120, v70, v71
	v_mul_f32_e32 v70, v5, v122
	v_mul_f32_e32 v71, v5, v123
	v_cvt_pk_bf16_f32 v121, v70, v71
	v_mul_f32_e32 v70, v136, v124
	v_mul_f32_e32 v71, v136, v125
	v_cvt_pk_bf16_f32 v124, v70, v71
	v_mul_f32_e32 v70, v136, v126
	v_mul_f32_e32 v71, v136, v127
	v_cvt_pk_bf16_f32 v125, v70, v71
	s_setprio 1
	v_mfma_f32_16x16x32_bf16 v[184:187], v[88:91], v[6:9], 0
	v_mfma_f32_16x16x32_bf16 v[88:91], v[88:91], v[22:25], 0
	s_waitcnt lgkmcnt(14)
	v_mfma_f32_16x16x32_bf16 v[184:187], v[92:95], v[10:13], v[184:187]
	v_mfma_f32_16x16x32_bf16 v[88:91], v[92:95], v[26:29], v[88:91]
	v_mfma_f32_16x16x32_bf16 v[92:95], v[96:99], v[14:17], v[184:187]
	v_mfma_f32_16x16x32_bf16 v[88:91], v[96:99], v[30:33], v[88:91]
	v_mfma_f32_16x16x32_bf16 v[92:95], v[100:103], v[18:21], v[92:95]
	v_mfma_f32_16x16x32_bf16 v[88:91], v[100:103], v[34:37], v[88:91]
	v_mfma_f32_16x16x32_bf16 v[92:95], v[104:107], v[38:41], v[92:95]
	v_mfma_f32_16x16x32_bf16 v[88:91], v[104:107], v[54:57], v[88:91]
	v_mfma_f32_16x16x32_bf16 v[92:95], v[108:111], v[42:45], v[92:95]
	v_mfma_f32_16x16x32_bf16 v[88:91], v[108:111], v[58:61], v[88:91]
	v_mfma_f32_16x16x32_bf16 v[92:95], v[112:115], v[46:49], v[92:95]
	v_mfma_f32_16x16x32_bf16 v[88:91], v[112:115], v[62:65], v[88:91]
	v_mfma_f32_16x16x32_bf16 v[92:95], v[116:119], v[50:53], v[92:95]
	v_mfma_f32_16x16x32_bf16 v[88:91], v[116:119], v[66:69], v[88:91]
	s_setprio 0
	s_nop 5
	v_mul_f32_e32 v70, v5, v92
	v_mul_f32_e32 v71, v5, v93
	v_cvt_pk_bf16_f32 v122, v70, v71
	v_mul_f32_e32 v70, v5, v94
	v_mul_f32_e32 v71, v5, v95
	v_cvt_pk_bf16_f32 v123, v70, v71
	v_mul_f32_e32 v70, v136, v88
	v_mul_f32_e32 v71, v136, v89
	v_cvt_pk_bf16_f32 v126, v70, v71
	v_mul_f32_e32 v70, v136, v90
	v_mul_f32_e32 v71, v136, v91
	v_cvt_pk_bf16_f32 v127, v70, v71
	global_store_dwordx4 v[2:3], v[120:123], off offset:64 sc1
	global_store_dwordx4 v[134:135], v[124:127], off offset:64 sc1
	ds_read_b64 v[88:89], v72 offset:34816
	ds_read_b64 v[90:91], v73 offset:34816
	ds_read_b64 v[92:93], v74 offset:34816
	ds_read_b64 v[94:95], v75 offset:34816
	ds_read_b64 v[96:97], v76 offset:34816
	ds_read_b64 v[98:99], v77 offset:34816
	ds_read_b64 v[100:101], v78 offset:34816
	ds_read_b64 v[102:103], v79 offset:34816
	ds_read_b64 v[104:105], v80 offset:34816
	ds_read_b64 v[106:107], v81 offset:34816
	ds_read_b64 v[108:109], v82 offset:34816
	ds_read_b64 v[110:111], v83 offset:34816
	ds_read_b64 v[112:113], v84 offset:34816
	ds_read_b64 v[114:115], v85 offset:34816
	ds_read_b64 v[116:117], v86 offset:34816
	ds_read_b64 v[118:119], v87 offset:34816
	s_setprio 1
	v_mfma_f32_16x16x32_bf16 v[120:123], v[128:131], v[6:9], 0
	v_mfma_f32_16x16x32_bf16 v[124:127], v[128:131], v[22:25], 0
	s_waitcnt lgkmcnt(14)
	v_mfma_f32_16x16x32_bf16 v[120:123], v[156:159], v[10:13], v[120:123]
	v_mfma_f32_16x16x32_bf16 v[124:127], v[156:159], v[26:29], v[124:127]
	v_mfma_f32_16x16x32_bf16 v[120:123], v[160:163], v[14:17], v[120:123]
	v_mfma_f32_16x16x32_bf16 v[124:127], v[160:163], v[30:33], v[124:127]
	v_mfma_f32_16x16x32_bf16 v[120:123], v[164:167], v[18:21], v[120:123]
	v_mfma_f32_16x16x32_bf16 v[124:127], v[164:167], v[34:37], v[124:127]
	v_mfma_f32_16x16x32_bf16 v[120:123], v[168:171], v[38:41], v[120:123]
	v_mfma_f32_16x16x32_bf16 v[124:127], v[168:171], v[54:57], v[124:127]
	v_mfma_f32_16x16x32_bf16 v[120:123], v[172:175], v[42:45], v[120:123]
	v_mfma_f32_16x16x32_bf16 v[124:127], v[172:175], v[58:61], v[124:127]
	v_mfma_f32_16x16x32_bf16 v[120:123], v[176:179], v[46:49], v[120:123]
	v_mfma_f32_16x16x32_bf16 v[124:127], v[176:179], v[62:65], v[124:127]
	v_mfma_f32_16x16x32_bf16 v[120:123], v[180:183], v[50:53], v[120:123]
	v_mfma_f32_16x16x32_bf16 v[124:127], v[180:183], v[66:69], v[124:127]
	s_setprio 0
	ds_read_b64 v[128:129], v72 offset:49152
	ds_read_b64 v[130:131], v73 offset:49152
	ds_read_b64 v[156:157], v74 offset:49152
	ds_read_b64 v[158:159], v75 offset:49152
	ds_read_b64 v[160:161], v76 offset:49152
	ds_read_b64 v[162:163], v77 offset:49152
	ds_read_b64 v[164:165], v78 offset:49152
	ds_read_b64 v[166:167], v79 offset:49152
	ds_read_b64 v[168:169], v80 offset:49152
	ds_read_b64 v[170:171], v81 offset:49152
	ds_read_b64 v[172:173], v82 offset:49152
	ds_read_b64 v[174:175], v83 offset:49152
	ds_read_b64 v[176:177], v84 offset:49152
	ds_read_b64 v[178:179], v85 offset:49152
	ds_read_b64 v[180:181], v86 offset:49152
	ds_read_b64 v[182:183], v87 offset:49152
	v_mul_f32_e32 v70, v5, v120
	v_mul_f32_e32 v71, v5, v121
	v_cvt_pk_bf16_f32 v120, v70, v71
	v_mul_f32_e32 v70, v5, v122
	v_mul_f32_e32 v71, v5, v123
	v_cvt_pk_bf16_f32 v121, v70, v71
	v_mul_f32_e32 v70, v136, v124
	v_mul_f32_e32 v71, v136, v125
	v_cvt_pk_bf16_f32 v124, v70, v71
	v_mul_f32_e32 v70, v136, v126
	v_mul_f32_e32 v71, v136, v127
	v_cvt_pk_bf16_f32 v125, v70, v71
	s_setprio 1
	v_mfma_f32_16x16x32_bf16 v[184:187], v[88:91], v[6:9], 0
	v_mfma_f32_16x16x32_bf16 v[88:91], v[88:91], v[22:25], 0
	s_waitcnt lgkmcnt(14)
	v_mfma_f32_16x16x32_bf16 v[184:187], v[92:95], v[10:13], v[184:187]
	v_mfma_f32_16x16x32_bf16 v[88:91], v[92:95], v[26:29], v[88:91]
	v_mfma_f32_16x16x32_bf16 v[92:95], v[96:99], v[14:17], v[184:187]
	v_mfma_f32_16x16x32_bf16 v[88:91], v[96:99], v[30:33], v[88:91]
	v_mfma_f32_16x16x32_bf16 v[92:95], v[100:103], v[18:21], v[92:95]
	v_mfma_f32_16x16x32_bf16 v[88:91], v[100:103], v[34:37], v[88:91]
	v_mfma_f32_16x16x32_bf16 v[92:95], v[104:107], v[38:41], v[92:95]
	v_mfma_f32_16x16x32_bf16 v[88:91], v[104:107], v[54:57], v[88:91]
	v_mfma_f32_16x16x32_bf16 v[92:95], v[108:111], v[42:45], v[92:95]
	v_mfma_f32_16x16x32_bf16 v[88:91], v[108:111], v[58:61], v[88:91]
	v_mfma_f32_16x16x32_bf16 v[92:95], v[112:115], v[46:49], v[92:95]
	v_mfma_f32_16x16x32_bf16 v[88:91], v[112:115], v[62:65], v[88:91]
	v_mfma_f32_16x16x32_bf16 v[92:95], v[116:119], v[50:53], v[92:95]
	v_mfma_f32_16x16x32_bf16 v[88:91], v[116:119], v[66:69], v[88:91]
	s_setprio 0
	s_nop 5
	v_mul_f32_e32 v70, v5, v92
	v_mul_f32_e32 v71, v5, v93
	v_cvt_pk_bf16_f32 v122, v70, v71
	v_mul_f32_e32 v70, v5, v94
	v_mul_f32_e32 v71, v5, v95
	v_cvt_pk_bf16_f32 v123, v70, v71
	v_mul_f32_e32 v70, v136, v88
	v_mul_f32_e32 v71, v136, v89
	v_cvt_pk_bf16_f32 v126, v70, v71
	v_mul_f32_e32 v70, v136, v90
	v_mul_f32_e32 v71, v136, v91
	v_cvt_pk_bf16_f32 v127, v70, v71
	global_store_dwordx4 v[2:3], v[120:123], off offset:128 sc1
	global_store_dwordx4 v[134:135], v[124:127], off offset:128 sc1
	ds_read_b64 v[70:71], v72 offset:51200
	ds_read_b64 v[72:73], v73 offset:51200
	ds_read_b64 v[88:89], v74 offset:51200
	ds_read_b64 v[90:91], v75 offset:51200
	ds_read_b64 v[74:75], v76 offset:51200
	ds_read_b64 v[76:77], v77 offset:51200
	ds_read_b64 v[92:93], v78 offset:51200
	ds_read_b64 v[94:95], v79 offset:51200
	ds_read_b64 v[78:79], v80 offset:51200
	ds_read_b64 v[80:81], v81 offset:51200
	ds_read_b64 v[96:97], v82 offset:51200
	ds_read_b64 v[98:99], v83 offset:51200
	ds_read_b64 v[82:83], v84 offset:51200
	ds_read_b64 v[84:85], v85 offset:51200
	ds_read_b64 v[100:101], v86 offset:51200
	ds_read_b64 v[102:103], v87 offset:51200
	s_setprio 1
	v_mfma_f32_16x16x32_bf16 v[104:107], v[128:131], v[6:9], 0
	v_mfma_f32_16x16x32_bf16 v[108:111], v[128:131], v[22:25], 0
	s_waitcnt lgkmcnt(14)
	v_mfma_f32_16x16x32_bf16 v[104:107], v[156:159], v[10:13], v[104:107]
	v_mfma_f32_16x16x32_bf16 v[108:111], v[156:159], v[26:29], v[108:111]
	v_mfma_f32_16x16x32_bf16 v[104:107], v[160:163], v[14:17], v[104:107]
	v_mfma_f32_16x16x32_bf16 v[108:111], v[160:163], v[30:33], v[108:111]
	v_mfma_f32_16x16x32_bf16 v[104:107], v[164:167], v[18:21], v[104:107]
	v_mfma_f32_16x16x32_bf16 v[108:111], v[164:167], v[34:37], v[108:111]
	v_mfma_f32_16x16x32_bf16 v[104:107], v[168:171], v[38:41], v[104:107]
	v_mfma_f32_16x16x32_bf16 v[108:111], v[168:171], v[54:57], v[108:111]
	v_mfma_f32_16x16x32_bf16 v[104:107], v[172:175], v[42:45], v[104:107]
	v_mfma_f32_16x16x32_bf16 v[108:111], v[172:175], v[58:61], v[108:111]
	v_mfma_f32_16x16x32_bf16 v[104:107], v[176:179], v[46:49], v[104:107]
	v_mfma_f32_16x16x32_bf16 v[108:111], v[176:179], v[62:65], v[108:111]
	v_mfma_f32_16x16x32_bf16 v[104:107], v[180:183], v[50:53], v[104:107]
	v_mfma_f32_16x16x32_bf16 v[108:111], v[180:183], v[66:69], v[108:111]
	s_setprio 0
	s_nop 5
	v_mul_f32_e32 v86, v5, v104
	v_mul_f32_e32 v87, v5, v105
	v_cvt_pk_bf16_f32 v86, v86, v87
	v_mul_f32_e32 v87, v5, v106
	v_mul_f32_e32 v104, v5, v107
	v_cvt_pk_bf16_f32 v87, v87, v104
	v_mul_f32_e32 v104, v136, v108
	v_mul_f32_e32 v105, v136, v109
	v_cvt_pk_bf16_f32 v104, v104, v105
	v_mul_f32_e32 v105, v136, v110
	v_mul_f32_e32 v106, v136, v111
	v_cvt_pk_bf16_f32 v105, v105, v106
	s_setprio 1
	v_mfma_f32_16x16x32_bf16 v[106:109], v[70:73], v[6:9], 0
	v_mfma_f32_16x16x32_bf16 v[70:73], v[70:73], v[22:25], 0
	s_waitcnt lgkmcnt(12)
	v_mfma_f32_16x16x32_bf16 v[106:109], v[88:91], v[10:13], v[106:109]
	v_mfma_f32_16x16x32_bf16 v[70:73], v[88:91], v[26:29], v[70:73]
	s_waitcnt lgkmcnt(10)
	v_mfma_f32_16x16x32_bf16 v[88:91], v[74:77], v[14:17], v[106:109]
	v_mfma_f32_16x16x32_bf16 v[70:73], v[74:77], v[30:33], v[70:73]
	s_waitcnt lgkmcnt(8)
	v_mfma_f32_16x16x32_bf16 v[74:77], v[92:95], v[18:21], v[88:91]
	v_mfma_f32_16x16x32_bf16 v[70:73], v[92:95], v[34:37], v[70:73]
	s_waitcnt lgkmcnt(6)
	v_mfma_f32_16x16x32_bf16 v[74:77], v[78:81], v[38:41], v[74:77]
	v_mfma_f32_16x16x32_bf16 v[70:73], v[78:81], v[54:57], v[70:73]
	s_waitcnt lgkmcnt(4)
	v_mfma_f32_16x16x32_bf16 v[74:77], v[96:99], v[42:45], v[74:77]
	v_mfma_f32_16x16x32_bf16 v[70:73], v[96:99], v[58:61], v[70:73]
	s_waitcnt lgkmcnt(2)
	v_mfma_f32_16x16x32_bf16 v[74:77], v[82:85], v[46:49], v[74:77]
	v_mfma_f32_16x16x32_bf16 v[70:73], v[82:85], v[62:65], v[70:73]
	s_waitcnt lgkmcnt(0)
	v_mfma_f32_16x16x32_bf16 v[74:77], v[100:103], v[50:53], v[74:77]
	v_mfma_f32_16x16x32_bf16 v[70:73], v[100:103], v[66:69], v[70:73]
	s_setprio 0
	s_nop 5
	v_mul_f32_e32 v74, v5, v74
	v_mul_f32_e32 v75, v5, v75
	v_mul_f32_e32 v70, v136, v70
	v_cvt_pk_bf16_f32 v88, v74, v75
	v_mul_f32_e32 v74, v5, v76
	v_mul_f32_e32 v75, v5, v77
	v_cvt_pk_bf16_f32 v89, v74, v75
	v_mul_f32_e32 v71, v136, v71
	v_cvt_pk_bf16_f32 v106, v70, v71
	v_mul_f32_e32 v70, v136, v72
	v_add_u32_e32 v78, 0x10000, v146
	v_mul_f32_e32 v71, v136, v73
	v_cvt_pk_bf16_f32 v107, v70, v71
	global_store_dwordx4 v[2:3], v[86:89], off offset:192 sc1
	global_store_dwordx4 v[134:135], v[104:107], off offset:192 sc1
	v_add_u32_e32 v70, v78, v149
	v_add_u32_e32 v72, v78, v151
	v_add_u32_e32 v74, v78, v153
	v_add_u32_e32 v76, v78, v154
	v_add_u32_e32 v79, v78, v143
	v_add_u32_e32 v80, v78, v147
	v_add_u32_e32 v81, v78, v150
	s_waitcnt vmcnt(8)
	s_barrier
	ds_read_b64 v[70:71], v70
	ds_read_b64 v[72:73], v72
	ds_read_b64 v[74:75], v74
	ds_read_b64 v[76:77], v76
	v_add_u32_e32 v86, v78, v152
	ds_read_b64 v[82:83], v79
	ds_read_b64 v[84:85], v80
	ds_read_b64 v[90:91], v81
	ds_read_b64 v[92:93], v86
	v_add_u32_e32 v79, v78, v139
	v_add_u32_e32 v80, v78, v141
	v_add_u32_e32 v81, v78, v145
	v_add_u32_e32 v86, v78, v148
	ds_read_b64 v[94:95], v79
	ds_read_b64 v[96:97], v80
	ds_read_b64 v[98:99], v81
	ds_read_b64 v[100:101], v86
	v_add_u32_e32 v79, v78, v137
	v_add_u32_e32 v80, v78, v138
	v_add_u32_e32 v81, v78, v140
	v_add_u32_e32 v78, v78, v142
	ds_read_b64 v[102:103], v79
	ds_read_b64 v[104:105], v80
	ds_read_b64 v[106:107], v81
	ds_read_b64 v[108:109], v78
	v_add_u32_e32 v78, 0x10800, v146
	v_add_u32_e32 v79, v78, v149
	v_add_u32_e32 v80, v78, v151
	v_add_u32_e32 v81, v78, v153
	v_add_u32_e32 v86, v78, v154
	ds_read_b64 v[110:111], v79
	ds_read_b64 v[112:113], v80
	ds_read_b64 v[118:119], v81
	ds_read_b64 v[120:121], v86
	v_add_u32_e32 v79, v78, v143
	v_add_u32_e32 v80, v78, v147
	v_add_u32_e32 v81, v78, v150
	v_add_u32_e32 v86, v78, v152
	ds_read_b64 v[126:127], v79
	ds_read_b64 v[128:129], v80
	ds_read_b64 v[130:131], v81
	ds_read_b64 v[132:133], v86
	v_add_u32_e32 v79, v78, v139
	v_add_u32_e32 v80, v78, v141
	v_add_u32_e32 v81, v78, v145
	v_add_u32_e32 v88, v78, v148
	ds_read_b64 v[156:157], v79
	ds_read_b64 v[158:159], v80
	ds_read_b64 v[86:87], v81
	ds_read_b64 v[88:89], v88
	v_add_u32_e32 v79, v78, v137
	v_add_u32_e32 v80, v78, v138
	v_add_u32_e32 v81, v78, v140
	v_add_u32_e32 v114, v78, v142
	ds_read_b64 v[160:161], v79
	ds_read_b64 v[162:163], v80
	ds_read_b64 v[78:79], v81
	ds_read_b64 v[80:81], v114
	s_setprio 1
	s_waitcnt lgkmcnt(14)
	v_mfma_f32_16x16x32_bf16 v[114:117], v[70:73], v[6:9], 0
	v_mfma_f32_16x16x32_bf16 v[70:73], v[70:73], v[22:25], 0
	v_mfma_f32_16x16x32_bf16 v[114:117], v[74:77], v[10:13], v[114:117]
	v_mfma_f32_16x16x32_bf16 v[70:73], v[74:77], v[26:29], v[70:73]
	v_mfma_f32_16x16x32_bf16 v[74:77], v[82:85], v[14:17], v[114:117]
	v_mfma_f32_16x16x32_bf16 v[70:73], v[82:85], v[30:33], v[70:73]
	v_mfma_f32_16x16x32_bf16 v[74:77], v[90:93], v[18:21], v[74:77]
	v_mfma_f32_16x16x32_bf16 v[70:73], v[90:93], v[34:37], v[70:73]
	v_mfma_f32_16x16x32_bf16 v[74:77], v[94:97], v[38:41], v[74:77]
	v_mfma_f32_16x16x32_bf16 v[70:73], v[94:97], v[54:57], v[70:73]
	v_mfma_f32_16x16x32_bf16 v[74:77], v[98:101], v[42:45], v[74:77]
	v_mfma_f32_16x16x32_bf16 v[70:73], v[98:101], v[58:61], v[70:73]
	v_mfma_f32_16x16x32_bf16 v[74:77], v[102:105], v[46:49], v[74:77]
	v_mfma_f32_16x16x32_bf16 v[70:73], v[102:105], v[62:65], v[70:73]
	v_mfma_f32_16x16x32_bf16 v[74:77], v[106:109], v[50:53], v[74:77]
	v_mfma_f32_16x16x32_bf16 v[70:73], v[106:109], v[66:69], v[70:73]
	s_setprio 0
	v_add_u32_e32 v96, 0x14000, v146
	v_add_u32_e32 v97, v96, v139
	ds_read_b64 v[98:99], v97
	v_add_u32_e32 v97, v96, v141
	ds_read_b64 v[100:101], v97
	v_add_u32_e32 v97, v96, v145
	ds_read_b64 v[106:107], v97
	v_add_u32_e32 v97, v96, v148
	v_mul_f32_e32 v74, v5, v74
	v_mul_f32_e32 v70, v136, v70
	ds_read_b64 v[108:109], v97
	v_add_u32_e32 v97, v96, v137
	v_mul_f32_e32 v75, v5, v75
	v_cvt_pk_bf16_f32 v94, v74, v75
	v_mul_f32_e32 v74, v5, v76
	v_mul_f32_e32 v71, v136, v71
	v_cvt_pk_bf16_f32 v102, v70, v71
	v_mul_f32_e32 v70, v136, v72
	ds_read_b64 v[114:115], v97
	v_add_u32_e32 v97, v96, v138
	v_mul_f32_e32 v75, v5, v77
	v_cvt_pk_bf16_f32 v95, v74, v75
	v_mul_f32_e32 v71, v136, v73
	v_cvt_pk_bf16_f32 v103, v70, v71
	v_add_u32_e32 v70, v96, v149
	v_add_u32_e32 v72, v96, v151
	v_add_u32_e32 v74, v96, v153
	v_add_u32_e32 v76, v96, v154
	v_add_u32_e32 v82, v96, v143
	v_add_u32_e32 v84, v96, v147
	v_add_u32_e32 v90, v96, v150
	v_add_u32_e32 v92, v96, v152
	ds_read_b64 v[116:117], v97
	v_add_u32_e32 v97, v96, v140
	v_add_u32_e32 v96, v96, v142
	ds_read_b64 v[70:71], v70
	ds_read_b64 v[72:73], v72
	ds_read_b64 v[74:75], v74
	ds_read_b64 v[76:77], v76
	ds_read_b64 v[82:83], v82
	ds_read_b64 v[84:85], v84
	ds_read_b64 v[90:91], v90
	ds_read_b64 v[92:93], v92
	ds_read_b64 v[122:123], v97
	ds_read_b64 v[124:125], v96
	s_setprio 1
	v_mfma_f32_16x16x32_bf16 v[164:167], v[110:113], v[6:9], 0
	v_mfma_f32_16x16x32_bf16 v[110:113], v[110:113], v[22:25], 0
	s_waitcnt lgkmcnt(14)
	v_mfma_f32_16x16x32_bf16 v[164:167], v[118:121], v[10:13], v[164:167]
	v_mfma_f32_16x16x32_bf16 v[110:113], v[118:121], v[26:29], v[110:113]
	v_mfma_f32_16x16x32_bf16 v[118:121], v[126:129], v[14:17], v[164:167]
	v_mfma_f32_16x16x32_bf16 v[110:113], v[126:129], v[30:33], v[110:113]
	v_mfma_f32_16x16x32_bf16 v[118:121], v[130:133], v[18:21], v[118:121]
	v_mfma_f32_16x16x32_bf16 v[110:113], v[130:133], v[34:37], v[110:113]
	v_mfma_f32_16x16x32_bf16 v[118:121], v[156:159], v[38:41], v[118:121]
	v_mfma_f32_16x16x32_bf16 v[110:113], v[156:159], v[54:57], v[110:113]
	v_mfma_f32_16x16x32_bf16 v[118:121], v[86:89], v[42:45], v[118:121]
	v_mfma_f32_16x16x32_bf16 v[86:89], v[86:89], v[58:61], v[110:113]
	v_mfma_f32_16x16x32_bf16 v[110:113], v[160:163], v[46:49], v[118:121]
	v_mfma_f32_16x16x32_bf16 v[86:89], v[160:163], v[62:65], v[86:89]
	v_mfma_f32_16x16x32_bf16 v[110:113], v[78:81], v[50:53], v[110:113]
	v_mfma_f32_16x16x32_bf16 v[78:81], v[78:81], v[66:69], v[86:89]
	s_setprio 0
	s_nop 5
	v_mul_f32_e32 v86, v5, v110
	v_mul_f32_e32 v87, v5, v111
	v_mul_f32_e32 v78, v136, v78
	v_cvt_pk_bf16_f32 v96, v86, v87
	v_mul_f32_e32 v86, v5, v112
	v_mul_f32_e32 v87, v5, v113
	v_cvt_pk_bf16_f32 v97, v86, v87
	v_mul_f32_e32 v79, v136, v79
	v_cvt_pk_bf16_f32 v104, v78, v79
	v_mul_f32_e32 v78, v136, v80
	v_add_u32_e32 v132, 0x14800, v146
	v_mul_f32_e32 v79, v136, v81
	v_cvt_pk_bf16_f32 v105, v78, v79
	global_store_dwordx4 v[2:3], v[94:97], off offset:256 sc1
	global_store_dwordx4 v[134:135], v[102:105], off offset:256 sc1
	v_add_u32_e32 v78, v132, v149
	v_add_u32_e32 v80, v132, v151
	v_add_u32_e32 v86, v132, v153
	v_add_u32_e32 v88, v132, v154
	v_add_u32_e32 v94, v132, v143
	v_add_u32_e32 v96, v132, v147
	v_add_u32_e32 v102, v132, v150
	v_add_u32_e32 v104, v132, v152
	v_add_u32_e32 v110, v132, v139
	v_add_u32_e32 v112, v132, v141
	v_add_u32_e32 v118, v132, v145
	v_add_u32_e32 v120, v132, v148
	v_add_u32_e32 v126, v132, v137
	v_add_u32_e32 v128, v132, v138
	v_add_u32_e32 v130, v132, v140
	v_add_u32_e32 v132, v132, v142
	ds_read_b64 v[78:79], v78
	ds_read_b64 v[80:81], v80
	ds_read_b64 v[86:87], v86
	ds_read_b64 v[88:89], v88
	ds_read_b64 v[94:95], v94
	ds_read_b64 v[96:97], v96
	ds_read_b64 v[102:103], v102
	ds_read_b64 v[104:105], v104
	ds_read_b64 v[110:111], v110
	ds_read_b64 v[112:113], v112
	ds_read_b64 v[118:119], v118
	ds_read_b64 v[120:121], v120
	ds_read_b64 v[126:127], v126
	ds_read_b64 v[128:129], v128
	ds_read_b64 v[130:131], v130
	ds_read_b64 v[132:133], v132
	s_setprio 1
	s_waitcnt lgkmcnt(14)
	v_mfma_f32_16x16x32_bf16 v[156:159], v[70:73], v[6:9], 0
	v_mfma_f32_16x16x32_bf16 v[70:73], v[70:73], v[22:25], 0
	v_mfma_f32_16x16x32_bf16 v[156:159], v[74:77], v[10:13], v[156:159]
	v_mfma_f32_16x16x32_bf16 v[70:73], v[74:77], v[26:29], v[70:73]
	v_mfma_f32_16x16x32_bf16 v[74:77], v[82:85], v[14:17], v[156:159]
	v_mfma_f32_16x16x32_bf16 v[70:73], v[82:85], v[30:33], v[70:73]
	v_mfma_f32_16x16x32_bf16 v[74:77], v[90:93], v[18:21], v[74:77]
	v_mfma_f32_16x16x32_bf16 v[70:73], v[90:93], v[34:37], v[70:73]
	v_mfma_f32_16x16x32_bf16 v[74:77], v[98:101], v[38:41], v[74:77]
	v_mfma_f32_16x16x32_bf16 v[70:73], v[98:101], v[54:57], v[70:73]
	v_mfma_f32_16x16x32_bf16 v[74:77], v[106:109], v[42:45], v[74:77]
	v_mfma_f32_16x16x32_bf16 v[70:73], v[106:109], v[58:61], v[70:73]
	v_mfma_f32_16x16x32_bf16 v[74:77], v[114:117], v[46:49], v[74:77]
	v_mfma_f32_16x16x32_bf16 v[70:73], v[114:117], v[62:65], v[70:73]
	v_mfma_f32_16x16x32_bf16 v[74:77], v[122:125], v[50:53], v[74:77]
	v_mfma_f32_16x16x32_bf16 v[70:73], v[122:125], v[66:69], v[70:73]
	s_setprio 0
	s_nop 5
	v_mul_f32_e32 v74, v5, v74
	v_mul_f32_e32 v70, v136, v70
	v_mul_f32_e32 v75, v5, v75
	v_cvt_pk_bf16_f32 v156, v74, v75
	v_mul_f32_e32 v74, v5, v76
	v_mul_f32_e32 v71, v136, v71
	v_cvt_pk_bf16_f32 v160, v70, v71
	v_mul_f32_e32 v70, v136, v72
	v_add_u32_e32 v124, 0x18000, v146
	v_mul_f32_e32 v75, v5, v77
	v_cvt_pk_bf16_f32 v157, v74, v75
	v_mul_f32_e32 v71, v136, v73
	v_cvt_pk_bf16_f32 v161, v70, v71
	v_add_u32_e32 v70, v124, v149
	v_add_u32_e32 v72, v124, v151
	v_add_u32_e32 v74, v124, v153
	v_add_u32_e32 v76, v124, v154
	v_add_u32_e32 v82, v124, v143
	v_add_u32_e32 v84, v124, v147
	v_add_u32_e32 v90, v124, v150
	v_add_u32_e32 v92, v124, v152
	v_add_u32_e32 v98, v124, v139
	v_add_u32_e32 v100, v124, v141
	v_add_u32_e32 v106, v124, v145
	v_add_u32_e32 v108, v124, v148
	v_add_u32_e32 v114, v124, v137
	v_add_u32_e32 v116, v124, v138
	v_add_u32_e32 v122, v124, v140
	v_add_u32_e32 v124, v124, v142
	ds_read_b64 v[70:71], v70
	ds_read_b64 v[72:73], v72
	ds_read_b64 v[74:75], v74
	ds_read_b64 v[76:77], v76
	ds_read_b64 v[82:83], v82
	ds_read_b64 v[84:85], v84
	ds_read_b64 v[90:91], v90
	ds_read_b64 v[92:93], v92
	ds_read_b64 v[98:99], v98
	ds_read_b64 v[100:101], v100
	ds_read_b64 v[106:107], v106
	ds_read_b64 v[108:109], v108
	ds_read_b64 v[114:115], v114
	ds_read_b64 v[116:117], v116
	ds_read_b64 v[122:123], v122
	ds_read_b64 v[124:125], v124
	s_setprio 1
	v_mfma_f32_16x16x32_bf16 v[162:165], v[78:81], v[6:9], 0
	v_mfma_f32_16x16x32_bf16 v[78:81], v[78:81], v[22:25], 0
	s_waitcnt lgkmcnt(14)
	v_mfma_f32_16x16x32_bf16 v[162:165], v[86:89], v[10:13], v[162:165]
	v_mfma_f32_16x16x32_bf16 v[78:81], v[86:89], v[26:29], v[78:81]
	v_mfma_f32_16x16x32_bf16 v[86:89], v[94:97], v[14:17], v[162:165]
	v_mfma_f32_16x16x32_bf16 v[78:81], v[94:97], v[30:33], v[78:81]
	v_mfma_f32_16x16x32_bf16 v[86:89], v[102:105], v[18:21], v[86:89]
	v_mfma_f32_16x16x32_bf16 v[78:81], v[102:105], v[34:37], v[78:81]
	v_mfma_f32_16x16x32_bf16 v[86:89], v[110:113], v[38:41], v[86:89]
	v_mfma_f32_16x16x32_bf16 v[78:81], v[110:113], v[54:57], v[78:81]
	v_mfma_f32_16x16x32_bf16 v[86:89], v[118:121], v[42:45], v[86:89]
	v_mfma_f32_16x16x32_bf16 v[78:81], v[118:121], v[58:61], v[78:81]
	v_mfma_f32_16x16x32_bf16 v[86:89], v[126:129], v[46:49], v[86:89]
	v_mfma_f32_16x16x32_bf16 v[78:81], v[126:129], v[62:65], v[78:81]
	v_mfma_f32_16x16x32_bf16 v[86:89], v[130:133], v[50:53], v[86:89]
	v_mfma_f32_16x16x32_bf16 v[78:81], v[130:133], v[66:69], v[78:81]
	s_setprio 0
	s_nop 5
	v_mul_f32_e32 v86, v5, v86
	v_mul_f32_e32 v87, v5, v87
	v_mul_f32_e32 v78, v136, v78
	v_cvt_pk_bf16_f32 v158, v86, v87
	v_mul_f32_e32 v86, v5, v88
	v_mul_f32_e32 v87, v5, v89
	v_cvt_pk_bf16_f32 v159, v86, v87
	v_mul_f32_e32 v79, v136, v79
	v_cvt_pk_bf16_f32 v162, v78, v79
	v_mul_f32_e32 v78, v136, v80
	v_add_u32_e32 v132, 0x18800, v146
	v_mul_f32_e32 v79, v136, v81
	v_cvt_pk_bf16_f32 v163, v78, v79
	global_store_dwordx4 v[2:3], v[156:159], off offset:320 sc1
	global_store_dwordx4 v[134:135], v[160:163], off offset:320 sc1
	v_add_u32_e32 v78, v132, v149
	v_add_u32_e32 v80, v132, v151
	v_add_u32_e32 v86, v132, v153
	v_add_u32_e32 v88, v132, v154
	v_add_u32_e32 v94, v132, v143
	v_add_u32_e32 v96, v132, v147
	v_add_u32_e32 v102, v132, v150
	v_add_u32_e32 v104, v132, v152
	v_add_u32_e32 v110, v132, v139
	v_add_u32_e32 v112, v132, v141
	v_add_u32_e32 v118, v132, v145
	v_add_u32_e32 v120, v132, v148
	v_add_u32_e32 v126, v132, v137
	v_add_u32_e32 v128, v132, v138
	v_add_u32_e32 v130, v132, v140
	v_add_u32_e32 v132, v132, v142
	ds_read_b64 v[78:79], v78
	ds_read_b64 v[80:81], v80
	ds_read_b64 v[86:87], v86
	ds_read_b64 v[88:89], v88
	ds_read_b64 v[94:95], v94
	ds_read_b64 v[96:97], v96
	ds_read_b64 v[102:103], v102
	ds_read_b64 v[104:105], v104
	ds_read_b64 v[110:111], v110
	ds_read_b64 v[112:113], v112
	ds_read_b64 v[118:119], v118
	ds_read_b64 v[120:121], v120
	ds_read_b64 v[126:127], v126
	ds_read_b64 v[128:129], v128
	ds_read_b64 v[130:131], v130
	ds_read_b64 v[132:133], v132
	s_setprio 1
	v_mfma_f32_16x16x32_bf16 v[156:159], v[70:73], v[6:9], 0
	v_mfma_f32_16x16x32_bf16 v[70:73], v[70:73], v[22:25], 0
	s_waitcnt lgkmcnt(14)
	v_mfma_f32_16x16x32_bf16 v[156:159], v[74:77], v[10:13], v[156:159]
	v_mfma_f32_16x16x32_bf16 v[70:73], v[74:77], v[26:29], v[70:73]
	v_mfma_f32_16x16x32_bf16 v[74:77], v[82:85], v[14:17], v[156:159]
	v_mfma_f32_16x16x32_bf16 v[70:73], v[82:85], v[30:33], v[70:73]
	v_mfma_f32_16x16x32_bf16 v[74:77], v[90:93], v[18:21], v[74:77]
	v_mfma_f32_16x16x32_bf16 v[70:73], v[90:93], v[34:37], v[70:73]
	v_mfma_f32_16x16x32_bf16 v[74:77], v[98:101], v[38:41], v[74:77]
	v_mfma_f32_16x16x32_bf16 v[70:73], v[98:101], v[54:57], v[70:73]
	v_mfma_f32_16x16x32_bf16 v[74:77], v[106:109], v[42:45], v[74:77]
	v_mfma_f32_16x16x32_bf16 v[70:73], v[106:109], v[58:61], v[70:73]
	v_mfma_f32_16x16x32_bf16 v[74:77], v[114:117], v[46:49], v[74:77]
	v_mfma_f32_16x16x32_bf16 v[70:73], v[114:117], v[62:65], v[70:73]
	v_mfma_f32_16x16x32_bf16 v[74:77], v[122:125], v[50:53], v[74:77]
	v_mfma_f32_16x16x32_bf16 v[70:73], v[122:125], v[66:69], v[70:73]
	s_setprio 0
	s_nop 5
	v_mul_f32_e32 v74, v5, v74
	v_mul_f32_e32 v70, v136, v70
	v_mul_f32_e32 v75, v5, v75
	v_cvt_pk_bf16_f32 v156, v74, v75
	v_mul_f32_e32 v74, v5, v76
	v_mul_f32_e32 v71, v136, v71
	v_cvt_pk_bf16_f32 v160, v70, v71
	v_mul_f32_e32 v70, v136, v72
	v_add_u32_e32 v124, 0x1c000, v146
	v_mul_f32_e32 v75, v5, v77
	v_cvt_pk_bf16_f32 v157, v74, v75
	v_mul_f32_e32 v71, v136, v73
	v_cvt_pk_bf16_f32 v161, v70, v71
	v_add_u32_e32 v70, v124, v149
	v_add_u32_e32 v72, v124, v151
	v_add_u32_e32 v74, v124, v153
	v_add_u32_e32 v76, v124, v154
	v_add_u32_e32 v82, v124, v143
	v_add_u32_e32 v84, v124, v147
	v_add_u32_e32 v90, v124, v150
	v_add_u32_e32 v92, v124, v152
	v_add_u32_e32 v98, v124, v139
	v_add_u32_e32 v100, v124, v141
	v_add_u32_e32 v106, v124, v145
	v_add_u32_e32 v108, v124, v148
	v_add_u32_e32 v114, v124, v137
	v_add_u32_e32 v116, v124, v138
	v_add_u32_e32 v122, v124, v140
	v_add_u32_e32 v124, v124, v142
	ds_read_b64 v[70:71], v70
	ds_read_b64 v[72:73], v72
	ds_read_b64 v[74:75], v74
	ds_read_b64 v[76:77], v76
	ds_read_b64 v[82:83], v82
	ds_read_b64 v[84:85], v84
	ds_read_b64 v[90:91], v90
	ds_read_b64 v[92:93], v92
	ds_read_b64 v[98:99], v98
	ds_read_b64 v[100:101], v100
	ds_read_b64 v[106:107], v106
	ds_read_b64 v[108:109], v108
	ds_read_b64 v[114:115], v114
	ds_read_b64 v[116:117], v116
	ds_read_b64 v[122:123], v122
	ds_read_b64 v[124:125], v124
	s_setprio 1
	v_mfma_f32_16x16x32_bf16 v[162:165], v[78:81], v[6:9], 0
	v_mfma_f32_16x16x32_bf16 v[78:81], v[78:81], v[22:25], 0
	s_waitcnt lgkmcnt(14)
	v_mfma_f32_16x16x32_bf16 v[162:165], v[86:89], v[10:13], v[162:165]
	v_mfma_f32_16x16x32_bf16 v[78:81], v[86:89], v[26:29], v[78:81]
	v_mfma_f32_16x16x32_bf16 v[86:89], v[94:97], v[14:17], v[162:165]
	v_mfma_f32_16x16x32_bf16 v[78:81], v[94:97], v[30:33], v[78:81]
	v_mfma_f32_16x16x32_bf16 v[86:89], v[102:105], v[18:21], v[86:89]
	v_mfma_f32_16x16x32_bf16 v[78:81], v[102:105], v[34:37], v[78:81]
	v_mfma_f32_16x16x32_bf16 v[86:89], v[110:113], v[38:41], v[86:89]
	v_mfma_f32_16x16x32_bf16 v[78:81], v[110:113], v[54:57], v[78:81]
	v_mfma_f32_16x16x32_bf16 v[86:89], v[118:121], v[42:45], v[86:89]
	v_mfma_f32_16x16x32_bf16 v[78:81], v[118:121], v[58:61], v[78:81]
	v_mfma_f32_16x16x32_bf16 v[86:89], v[126:129], v[46:49], v[86:89]
	v_mfma_f32_16x16x32_bf16 v[78:81], v[126:129], v[62:65], v[78:81]
	v_mfma_f32_16x16x32_bf16 v[86:89], v[130:133], v[50:53], v[86:89]
	v_mfma_f32_16x16x32_bf16 v[78:81], v[130:133], v[66:69], v[78:81]
	s_setprio 0
	s_nop 5
	v_mul_f32_e32 v86, v5, v86
	v_mul_f32_e32 v87, v5, v87
	v_mul_f32_e32 v78, v136, v78
	v_cvt_pk_bf16_f32 v158, v86, v87
	v_mul_f32_e32 v86, v5, v88
	v_mul_f32_e32 v87, v5, v89
	v_cvt_pk_bf16_f32 v159, v86, v87
	v_mul_f32_e32 v79, v136, v79
	v_cvt_pk_bf16_f32 v162, v78, v79
	v_mul_f32_e32 v78, v136, v80
	v_add_u32_e32 v132, 0x1c800, v146
	v_mul_f32_e32 v79, v136, v81
	v_cvt_pk_bf16_f32 v163, v78, v79
	global_store_dwordx4 v[2:3], v[156:159], off offset:384 sc1
	global_store_dwordx4 v[134:135], v[160:163], off offset:384 sc1
	v_add_u32_e32 v78, v132, v149
	v_add_u32_e32 v80, v132, v151
	v_add_u32_e32 v86, v132, v153
	v_add_u32_e32 v88, v132, v154
	v_add_u32_e32 v94, v132, v143
	v_add_u32_e32 v96, v132, v147
	v_add_u32_e32 v102, v132, v150
	v_add_u32_e32 v104, v132, v152
	v_add_u32_e32 v110, v132, v139
	v_add_u32_e32 v112, v132, v141
	v_add_u32_e32 v118, v132, v145
	v_add_u32_e32 v120, v132, v148
	v_add_u32_e32 v126, v132, v137
	v_add_u32_e32 v128, v132, v138
	v_add_u32_e32 v130, v132, v140
	v_add_u32_e32 v132, v132, v142
	ds_read_b64 v[78:79], v78
	ds_read_b64 v[80:81], v80
	ds_read_b64 v[86:87], v86
	ds_read_b64 v[88:89], v88
	ds_read_b64 v[94:95], v94
	ds_read_b64 v[96:97], v96
	ds_read_b64 v[102:103], v102
	ds_read_b64 v[104:105], v104
	ds_read_b64 v[110:111], v110
	ds_read_b64 v[112:113], v112
	ds_read_b64 v[118:119], v118
	ds_read_b64 v[120:121], v120
	ds_read_b64 v[126:127], v126
	ds_read_b64 v[128:129], v128
	ds_read_b64 v[130:131], v130
	ds_read_b64 v[132:133], v132
	s_setprio 1
	v_mfma_f32_16x16x32_bf16 v[138:141], v[70:73], v[6:9], 0
	v_mfma_f32_16x16x32_bf16 v[70:73], v[70:73], v[22:25], 0
	s_waitcnt lgkmcnt(14)
	v_mfma_f32_16x16x32_bf16 v[138:141], v[74:77], v[10:13], v[138:141]
	v_mfma_f32_16x16x32_bf16 v[70:73], v[74:77], v[26:29], v[70:73]
	v_mfma_f32_16x16x32_bf16 v[74:77], v[82:85], v[14:17], v[138:141]
	v_mfma_f32_16x16x32_bf16 v[70:73], v[82:85], v[30:33], v[70:73]
	v_mfma_f32_16x16x32_bf16 v[74:77], v[90:93], v[18:21], v[74:77]
	v_mfma_f32_16x16x32_bf16 v[70:73], v[90:93], v[34:37], v[70:73]
	v_mfma_f32_16x16x32_bf16 v[74:77], v[98:101], v[38:41], v[74:77]
	v_mfma_f32_16x16x32_bf16 v[70:73], v[98:101], v[54:57], v[70:73]
	v_mfma_f32_16x16x32_bf16 v[74:77], v[106:109], v[42:45], v[74:77]
	v_mfma_f32_16x16x32_bf16 v[70:73], v[106:109], v[58:61], v[70:73]
	v_mfma_f32_16x16x32_bf16 v[74:77], v[114:117], v[46:49], v[74:77]
	v_mfma_f32_16x16x32_bf16 v[70:73], v[114:117], v[62:65], v[70:73]
	v_mfma_f32_16x16x32_bf16 v[74:77], v[122:125], v[50:53], v[74:77]
	v_mfma_f32_16x16x32_bf16 v[70:73], v[122:125], v[66:69], v[70:73]
	s_setprio 0
	s_nop 5
	v_mul_f32_e32 v74, v5, v74
	v_mul_f32_e32 v75, v5, v75
	v_mul_f32_e32 v70, v136, v70
	v_mul_f32_e32 v71, v136, v71
	v_cvt_pk_bf16_f32 v74, v74, v75
	v_mul_f32_e32 v75, v5, v76
	v_cvt_pk_bf16_f32 v70, v70, v71
	v_mul_f32_e32 v71, v136, v72
	v_mul_f32_e32 v76, v5, v77
	v_cvt_pk_bf16_f32 v75, v75, v76
	v_mul_f32_e32 v72, v136, v73
	v_cvt_pk_bf16_f32 v71, v71, v72
	s_setprio 1
	v_mfma_f32_16x16x32_bf16 v[6:9], v[78:81], v[6:9], 0
	v_mfma_f32_16x16x32_bf16 v[22:25], v[78:81], v[22:25], 0
	s_waitcnt lgkmcnt(12)
	v_mfma_f32_16x16x32_bf16 v[6:9], v[86:89], v[10:13], v[6:9]
	v_mfma_f32_16x16x32_bf16 v[10:13], v[86:89], v[26:29], v[22:25]
	s_waitcnt lgkmcnt(10)
	v_mfma_f32_16x16x32_bf16 v[6:9], v[94:97], v[14:17], v[6:9]
	v_mfma_f32_16x16x32_bf16 v[10:13], v[94:97], v[30:33], v[10:13]
	s_waitcnt lgkmcnt(8)
	v_mfma_f32_16x16x32_bf16 v[6:9], v[102:105], v[18:21], v[6:9]
	v_mfma_f32_16x16x32_bf16 v[10:13], v[102:105], v[34:37], v[10:13]
	s_waitcnt lgkmcnt(6)
	v_mfma_f32_16x16x32_bf16 v[6:9], v[110:113], v[38:41], v[6:9]
	v_mfma_f32_16x16x32_bf16 v[10:13], v[110:113], v[54:57], v[10:13]
	s_waitcnt lgkmcnt(4)
	v_mfma_f32_16x16x32_bf16 v[6:9], v[118:121], v[42:45], v[6:9]
	v_mfma_f32_16x16x32_bf16 v[10:13], v[118:121], v[58:61], v[10:13]
	s_waitcnt lgkmcnt(2)
	v_mfma_f32_16x16x32_bf16 v[6:9], v[126:129], v[46:49], v[6:9]
	v_mfma_f32_16x16x32_bf16 v[10:13], v[126:129], v[62:65], v[10:13]
	s_waitcnt lgkmcnt(0)
	v_mfma_f32_16x16x32_bf16 v[6:9], v[130:133], v[50:53], v[6:9]
	v_mfma_f32_16x16x32_bf16 v[10:13], v[130:133], v[66:69], v[10:13]
	s_setprio 0
	s_nop 5
	v_mul_f32_e32 v6, v5, v6
	v_mul_f32_e32 v7, v5, v7
	v_cvt_pk_bf16_f32 v76, v6, v7
	v_mul_f32_e32 v6, v5, v8
	v_mul_f32_e32 v5, v5, v9
	v_cvt_pk_bf16_f32 v77, v6, v5
	v_mul_f32_e32 v5, v136, v10
	v_mul_f32_e32 v6, v136, v11
	v_cvt_pk_bf16_f32 v72, v5, v6
	v_mul_f32_e32 v5, v136, v12
	v_mul_f32_e32 v6, v136, v13
	v_cvt_pk_bf16_f32 v73, v5, v6
	global_store_dwordx4 v[2:3], v[74:77], off offset:448 sc1
	global_store_dwordx4 v[134:135], v[70:73], off offset:448 sc1
	s_barrier
